# sec 7.11 back-edge rotation on the 5 GEMM K-loops: next-iteration last/non-last selection done before the loop-back barrier, exit path gets its own barrier
# speedup vs baseline: 1.0153x; 1.0029x over previous
; #define PG8_STAGE(bufoff, gbase, v0, v1) do { \
;         __builtin_amdgcn_global_load_lds((const unsigned*)((const char*)(gbase) + (v0)), (LAS unsigned*)(lds + (bufoff) + ldsw), 16, 0, 0); \
;         __builtin_amdgcn_global_load_lds((const unsigned*)((const char*)(gbase) + (v1)), (LAS unsigned*)(lds + (bufoff) + ldsw + 8192), 16, 0, 0); } while (0)
; #define PG8_LDA(dst, b, h) do { _Pragma("unroll") for (int m = 0; m < 4; ++m) _Pragma("unroll") for (int k = 0; k < 2; ++k) dst[m][k] = *(const LAS bf16x8*)(lds + PG8_SA(b, h) + aoff + m * 2048 + k * 1024); } while (0)
; #define PG8_LDB(dst, b, h) do { _Pragma("unroll") for (int n = 0; n < 2; ++n) _Pragma("unroll") for (int k = 0; k < 2; ++k) dst[n][k] = *(const LAS bf16x8*)(lds + PG8_SB(b, h) + boff + n * 2048 + k * 1024); } while (0)
; #define PG8_MMA(ai, bj, At, Bt) do { __builtin_amdgcn_s_setprio(1); _Pragma("unroll") for (int m = 0; m < 4; ++m) _Pragma("unroll") for (int n = 0; n < 2; ++n) _Pragma("unroll") for (int k = 0; k < 2; ++k) \
;         acc[ai][bj][m][n] = __builtin_amdgcn_mfma_f32_16x16x32_bf16(Bt[n][k], At[m][k], acc[ai][bj][m][n], 0, 0, 0); __builtin_amdgcn_s_setprio(0); } while (0)
; #define PG8_WAIT_L(n) asm volatile("s_waitcnt lgkmcnt(" #n ")" ::: "memory")
; template <class Epi, class Sched>
; __device__ __forceinline__ void gemm_phase(LAS unsigned char* lds, const Sched& S, const Epi& E) {
;     ...
;             const bool last = (t == nt - 2);
;             const char* a1 = cA + (size_t)(t + 1) * kstep;
;             const char* a2 = last ? nA : cA + (size_t)(t + 2) * kstep; const char* b2 = last ? nB : cB + (size_t)(t + 2) * kstep;
;             const char* a3 = a2 + kstep; const char* b3 = b2 + kstep;
;             const unsigned xA0 = last ? nvA0 : vA0, xA1 = last ? nvA1 : vA1, xB0 = last ? nvB0 : vB0, xB1 = last ? nvB1 : vB1;
;             const size_t xhA = last ? nhA : hA, xhB = last ? nhB : hB;
;             PG8_LDB(B0, 0, 0); PG8_SCHED; PG8_LDA(At, 0, 0); PG8_STAGE(PG8_SA(1, 1), a1 + hA, vA0, vA1);
;             PG8_WAIT_L(8); PG8_BAR; PG8_WAIT_L(0); PG8_MMA(0, 0, At, B0); PG8_BAR; PG8_SCHED;
;             PG8_LDB(B1, 0, 1); PG8_STAGE(PG8_SB(0, 0), b2, xB0, xB1);
;             PG8_BAR; PG8_WAIT_L(0); PG8_MMA(0, 1, At, B1); PG8_BAR;
;             PG8_LDA(At, 0, 1); PG8_STAGE(PG8_SA(0, 0), a2, xA0, xA1);
;             PG8_BAR; PG8_WAIT_L(0); PG8_MMA(1, 0, At, B0); PG8_BAR; PG8_SCHED;
.LBB0_306:
	s_add_u32 s21, s26, 0xfff80080
	s_addc_u32 s69, s27, -1
	s_and_b64 s[40:41], exec, s[40:41]
	s_cselect_b32 s41, s23, s69
	s_cselect_b32 s40, s22, s21
	s_add_i32 s21, 0, 0x10000
	v_add_u32_e32 v138, s21, v153
	ds_read_b128 v[158:161], v138
	ds_read_b128 v[182:185], v138 offset:1024
	ds_read_b128 v[186:189], v138 offset:2048
	ds_read_b128 v[190:193], v138 offset:3072
	v_lshl_add_u64 v[226:227], s[26:27], 0, v[132:133]
	s_add_i32 m0, s48, 0xc000
	ds_read_b128 v[194:197], v154
	ds_read_b128 v[198:201], v154 offset:1024
	ds_read_b128 v[202:205], v154 offset:2048
	ds_read_b128 v[206:209], v154 offset:3072
	ds_read_b128 v[210:213], v154 offset:4096
	ds_read_b128 v[214:217], v154 offset:5120
	ds_read_b128 v[218:221], v154 offset:6144
	ds_read_b128 v[222:225], v154 offset:7168
	global_load_lds_dwordx4 v[226:227], off
	v_lshl_add_u64 v[226:227], s[26:27], 0, v[134:135]
	s_add_i32 m0, s48, 0xe000
	s_nop 0
	global_load_lds_dwordx4 v[226:227], off
	s_waitcnt lgkmcnt(8)
	s_barrier
	s_waitcnt lgkmcnt(0)
	s_setprio 1
	s_waitcnt lgkmcnt(0)
	v_mfma_f32_16x16x32_bf16 v[124:127], v[158:161], v[194:197], v[124:127]
	v_mfma_f32_16x16x32_bf16 v[120:123], v[186:189], v[194:197], v[120:123]
	v_mfma_f32_16x16x32_bf16 v[116:119], v[158:161], v[202:205], v[116:119]
	v_mfma_f32_16x16x32_bf16 v[112:115], v[186:189], v[202:205], v[112:115]
	v_mfma_f32_16x16x32_bf16 v[100:103], v[158:161], v[210:213], v[100:103]
	v_mfma_f32_16x16x32_bf16 v[96:99], v[186:189], v[210:213], v[96:99]
	v_mfma_f32_16x16x32_bf16 v[84:87], v[158:161], v[218:221], v[84:87]
	v_mfma_f32_16x16x32_bf16 v[80:83], v[186:189], v[218:221], v[80:83]
	v_mfma_f32_16x16x32_bf16 v[124:127], v[182:185], v[198:201], v[124:127]
	v_mfma_f32_16x16x32_bf16 v[120:123], v[190:193], v[198:201], v[120:123]
	v_mfma_f32_16x16x32_bf16 v[116:119], v[182:185], v[206:209], v[116:119]
	v_mfma_f32_16x16x32_bf16 v[112:115], v[190:193], v[206:209], v[112:115]
	v_mfma_f32_16x16x32_bf16 v[100:103], v[182:185], v[214:217], v[100:103]
	v_mfma_f32_16x16x32_bf16 v[96:99], v[190:193], v[214:217], v[96:99]
	v_mfma_f32_16x16x32_bf16 v[84:87], v[182:185], v[222:225], v[84:87]
	v_mfma_f32_16x16x32_bf16 v[80:83], v[190:193], v[222:225], v[80:83]
	s_setprio 0
	s_barrier
	s_add_i32 s69, 0, 0x14000
	s_add_i32 s21, s21, s43
	v_add_u32_e32 v138, s69, v153
	s_mov_b32 m0, s21
	ds_read_b128 v[226:229], v138
	ds_read_b128 v[230:233], v138 offset:1024
	ds_read_b128 v[234:237], v138 offset:2048
	ds_read_b128 v[238:241], v138 offset:3072
	global_load_lds_dwordx4 v136, s[38:39]
	s_add_i32 m0, s21, 0x2000
	v_mov_b32_e32 v147, v137
	global_load_lds_dwordx4 v146, s[38:39]
	s_barrier
	s_waitcnt lgkmcnt(0)
	v_lshl_add_u64 v[242:243], s[38:39], 0, v[136:137]
	v_lshl_add_u64 v[244:245], s[38:39], 0, v[146:147]
	s_setprio 1
	s_waitcnt lgkmcnt(0)
	v_mfma_f32_16x16x32_bf16 v[108:111], v[226:229], v[194:197], v[108:111]
	v_mfma_f32_16x16x32_bf16 v[104:107], v[234:237], v[194:197], v[104:107]
	v_mfma_f32_16x16x32_bf16 v[92:95], v[226:229], v[202:205], v[92:95]
	v_mfma_f32_16x16x32_bf16 v[88:91], v[234:237], v[202:205], v[88:91]
	v_mfma_f32_16x16x32_bf16 v[76:79], v[226:229], v[210:213], v[76:79]
	v_mfma_f32_16x16x32_bf16 v[72:75], v[234:237], v[210:213], v[72:75]
	v_mfma_f32_16x16x32_bf16 v[68:71], v[226:229], v[218:221], v[68:71]
	v_mfma_f32_16x16x32_bf16 v[64:67], v[234:237], v[218:221], v[64:67]
	v_mfma_f32_16x16x32_bf16 v[108:111], v[230:233], v[198:201], v[108:111]
	v_mfma_f32_16x16x32_bf16 v[104:107], v[238:241], v[198:201], v[104:107]
	v_mfma_f32_16x16x32_bf16 v[92:95], v[230:233], v[206:209], v[92:95]
	v_mfma_f32_16x16x32_bf16 v[88:91], v[238:241], v[206:209], v[88:91]
	v_mfma_f32_16x16x32_bf16 v[76:79], v[230:233], v[214:217], v[76:79]
	v_mfma_f32_16x16x32_bf16 v[72:75], v[238:241], v[214:217], v[72:75]
	v_mfma_f32_16x16x32_bf16 v[68:71], v[230:233], v[222:225], v[68:71]
	v_mfma_f32_16x16x32_bf16 v[64:67], v[238:241], v[222:225], v[64:67]
	s_setprio 0
	s_mov_b32 m0, s48
	v_lshl_add_u64 v[246:247], s[40:41], 0, v[150:151]
	s_barrier
	ds_read_b128 v[194:197], v154 offset:16384
	ds_read_b128 v[198:201], v154 offset:17408
	ds_read_b128 v[202:205], v154 offset:18432
	ds_read_b128 v[206:209], v154 offset:19456
	ds_read_b128 v[210:213], v154 offset:20480
	ds_read_b128 v[214:217], v154 offset:21504
	ds_read_b128 v[218:221], v154 offset:22528
	ds_read_b128 v[222:225], v154 offset:23552
	global_load_lds_dwordx4 v[246:247], off
	v_lshl_add_u64 v[248:249], s[40:41], 0, v[148:149]
	s_mov_b32 m0, s49
	s_nop 0
	global_load_lds_dwordx4 v[248:249], off
	s_barrier
	s_waitcnt lgkmcnt(0)
	s_setprio 1
	s_waitcnt lgkmcnt(0)
	v_mfma_f32_16x16x32_bf16 v[60:63], v[158:161], v[194:197], v[60:63]
	v_mfma_f32_16x16x32_bf16 v[56:59], v[186:189], v[194:197], v[56:59]
	v_mfma_f32_16x16x32_bf16 v[52:55], v[158:161], v[202:205], v[52:55]
	v_mfma_f32_16x16x32_bf16 v[44:47], v[186:189], v[202:205], v[44:47]
	v_mfma_f32_16x16x32_bf16 v[36:39], v[158:161], v[210:213], v[36:39]
	v_mfma_f32_16x16x32_bf16 v[28:31], v[186:189], v[210:213], v[28:31]
	v_mfma_f32_16x16x32_bf16 v[20:23], v[158:161], v[218:221], v[20:23]
	v_mfma_f32_16x16x32_bf16 v[12:15], v[186:189], v[218:221], v[12:15]
	v_mfma_f32_16x16x32_bf16 v[60:63], v[182:185], v[198:201], v[60:63]
	v_mfma_f32_16x16x32_bf16 v[56:59], v[190:193], v[198:201], v[56:59]
	v_mfma_f32_16x16x32_bf16 v[52:55], v[182:185], v[206:209], v[52:55]
	v_mfma_f32_16x16x32_bf16 v[44:47], v[190:193], v[206:209], v[44:47]
	v_mfma_f32_16x16x32_bf16 v[36:39], v[182:185], v[214:217], v[36:39]
	v_mfma_f32_16x16x32_bf16 v[28:31], v[190:193], v[214:217], v[28:31]
	v_mfma_f32_16x16x32_bf16 v[20:23], v[182:185], v[222:225], v[20:23]
	v_mfma_f32_16x16x32_bf16 v[12:15], v[190:193], v[222:225], v[12:15]
	s_setprio 0
	s_barrier
; #define PG8_STAGE(bufoff, gbase, v0, v1) do { \
;         __builtin_amdgcn_global_load_lds((const unsigned*)((const char*)(gbase) + (v0)), (LAS unsigned*)(lds + (bufoff) + ldsw), 16, 0, 0); \
;         __builtin_amdgcn_global_load_lds((const unsigned*)((const char*)(gbase) + (v1)), (LAS unsigned*)(lds + (bufoff) + ldsw + 8192), 16, 0, 0); } while (0)
; #define PG8_LDA(dst, b, h) do { _Pragma("unroll") for (int m = 0; m < 4; ++m) _Pragma("unroll") for (int k = 0; k < 2; ++k) dst[m][k] = *(const LAS bf16x8*)(lds + PG8_SA(b, h) + aoff + m * 2048 + k * 1024); } while (0)
; #define PG8_LDB(dst, b, h) do { _Pragma("unroll") for (int n = 0; n < 2; ++n) _Pragma("unroll") for (int k = 0; k < 2; ++k) dst[n][k] = *(const LAS bf16x8*)(lds + PG8_SB(b, h) + boff + n * 2048 + k * 1024); } while (0)
; #define PG8_MMA(ai, bj, At, Bt) do { __builtin_amdgcn_s_setprio(1); _Pragma("unroll") for (int m = 0; m < 4; ++m) _Pragma("unroll") for (int n = 0; n < 2; ++n) _Pragma("unroll") for (int k = 0; k < 2; ++k) \
;         acc[ai][bj][m][n] = __builtin_amdgcn_mfma_f32_16x16x32_bf16(Bt[n][k], At[m][k], acc[ai][bj][m][n], 0, 0, 0); __builtin_amdgcn_s_setprio(0); } while (0)
; #define PG8_WAIT_V(n) asm volatile("s_waitcnt vmcnt(" #n ")" ::: "memory")
; #define PG8_WAIT_L(n) asm volatile("s_waitcnt lgkmcnt(" #n ")" ::: "memory")
; #define PG8_BAR __builtin_amdgcn_s_barrier()
; #define PG8_SCHED __builtin_amdgcn_sched_barrier(0)
; template <class Epi, class Sched>
; __device__ __forceinline__ void gemm_phase(LAS unsigned char* lds, const Sched& S, const Epi& E) {
;     ...
;             PG8_STAGE(PG8_SB(0, 1), b2 + xhB, xB0, xB1);
;             PG8_WAIT_V(6); PG8_BAR; PG8_MMA(1, 1, At, B1); PG8_BAR;
;             PG8_LDB(B0, 1, 0); PG8_SCHED; PG8_LDA(At, 1, 0); PG8_STAGE(PG8_SA(0, 1), a2 + xhA, xA0, xA1);
;             PG8_WAIT_L(8); PG8_BAR; PG8_WAIT_L(0); PG8_MMA(0, 0, At, B0); PG8_BAR; PG8_SCHED;
;             PG8_LDB(B1, 1, 1); PG8_STAGE(PG8_SB(1, 0), b3, xB0, xB1);
	s_add_u32 s70, s38, 0x80000
	s_addc_u32 s71, s39, 0
	s_add_i32 s21, s69, s43
	s_mov_b32 m0, s21
	s_nop 0
	global_load_lds_dwordx4 v136, s[70:71]
	s_add_i32 m0, s21, 0x2000
	s_nop 0
	global_load_lds_dwordx4 v146, s[70:71]
	s_waitcnt vmcnt(6)
	s_barrier
	s_setprio 1
	v_mfma_f32_16x16x32_bf16 v[48:51], v[226:229], v[194:197], v[48:51]
	v_mfma_f32_16x16x32_bf16 v[40:43], v[234:237], v[194:197], v[40:43]
	v_mfma_f32_16x16x32_bf16 v[32:35], v[226:229], v[202:205], v[32:35]
	v_mfma_f32_16x16x32_bf16 v[24:27], v[234:237], v[202:205], v[24:27]
	v_mfma_f32_16x16x32_bf16 v[16:19], v[226:229], v[210:213], v[16:19]
	v_mfma_f32_16x16x32_bf16 v[8:11], v[234:237], v[210:213], v[8:11]
	v_mfma_f32_16x16x32_bf16 v[4:7], v[226:229], v[218:221], v[4:7]
	v_mfma_f32_16x16x32_bf16 v[0:3], v[234:237], v[218:221], v[0:3]
	v_mfma_f32_16x16x32_bf16 v[48:51], v[230:233], v[198:201], v[48:51]
	v_mfma_f32_16x16x32_bf16 v[40:43], v[238:241], v[198:201], v[40:43]
	v_mfma_f32_16x16x32_bf16 v[32:35], v[230:233], v[206:209], v[32:35]
	v_mfma_f32_16x16x32_bf16 v[24:27], v[238:241], v[206:209], v[24:27]
	v_mfma_f32_16x16x32_bf16 v[16:19], v[230:233], v[214:217], v[16:19]
	v_mfma_f32_16x16x32_bf16 v[8:11], v[238:241], v[214:217], v[8:11]
	v_mfma_f32_16x16x32_bf16 v[4:7], v[230:233], v[222:225], v[4:7]
	v_mfma_f32_16x16x32_bf16 v[0:3], v[238:241], v[222:225], v[0:3]
	s_setprio 0
	s_add_i32 s21, 0, 0x18000
	v_add_u32_e32 v138, s21, v153
	s_barrier
	ds_read_b128 v[158:161], v138
	ds_read_b128 v[182:185], v138 offset:1024
	ds_read_b128 v[186:189], v138 offset:2048
	ds_read_b128 v[190:193], v138 offset:3072
	s_add_u32 s40, s40, 0x80000
	s_addc_u32 s41, s41, 0
	s_mov_b32 m0, s50
	v_lshl_add_u64 v[150:151], s[40:41], 0, v[150:151]
	ds_read_b128 v[194:197], v154 offset:32768
	ds_read_b128 v[198:201], v154 offset:33792
	ds_read_b128 v[202:205], v154 offset:34816
	ds_read_b128 v[206:209], v154 offset:35840
	ds_read_b128 v[210:213], v154 offset:36864
	ds_read_b128 v[214:217], v154 offset:37888
	ds_read_b128 v[218:221], v154 offset:38912
	ds_read_b128 v[222:225], v154 offset:39936
	global_load_lds_dwordx4 v[150:151], off
	v_lshl_add_u64 v[148:149], s[40:41], 0, v[148:149]
	s_mov_b32 m0, s51
	s_nop 0
	global_load_lds_dwordx4 v[148:149], off
	s_waitcnt lgkmcnt(8)
	s_barrier
	s_waitcnt lgkmcnt(0)
	s_setprio 1
	s_waitcnt lgkmcnt(0)
	v_mfma_f32_16x16x32_bf16 v[124:127], v[158:161], v[194:197], v[124:127]
	v_mfma_f32_16x16x32_bf16 v[120:123], v[186:189], v[194:197], v[120:123]
	v_mfma_f32_16x16x32_bf16 v[116:119], v[158:161], v[202:205], v[116:119]
	v_mfma_f32_16x16x32_bf16 v[112:115], v[186:189], v[202:205], v[112:115]
	v_mfma_f32_16x16x32_bf16 v[100:103], v[158:161], v[210:213], v[100:103]
	v_mfma_f32_16x16x32_bf16 v[96:99], v[186:189], v[210:213], v[96:99]
	v_mfma_f32_16x16x32_bf16 v[84:87], v[158:161], v[218:221], v[84:87]
	v_mfma_f32_16x16x32_bf16 v[80:83], v[186:189], v[218:221], v[80:83]
	v_mfma_f32_16x16x32_bf16 v[124:127], v[182:185], v[198:201], v[124:127]
	v_mfma_f32_16x16x32_bf16 v[120:123], v[190:193], v[198:201], v[120:123]
	v_mfma_f32_16x16x32_bf16 v[116:119], v[182:185], v[206:209], v[116:119]
	v_mfma_f32_16x16x32_bf16 v[112:115], v[190:193], v[206:209], v[112:115]
	v_mfma_f32_16x16x32_bf16 v[100:103], v[182:185], v[214:217], v[100:103]
	v_mfma_f32_16x16x32_bf16 v[96:99], v[190:193], v[214:217], v[96:99]
	v_mfma_f32_16x16x32_bf16 v[84:87], v[182:185], v[222:225], v[84:87]
	v_mfma_f32_16x16x32_bf16 v[80:83], v[190:193], v[222:225], v[80:83]
	s_setprio 0
	s_barrier
	s_add_i32 s40, 0, 0x1c000
	s_add_i32 s21, s21, s43
	v_add_u32_e32 v138, s40, v153
	v_lshl_add_u64 v[238:239], v[242:243], 0, s[44:45]
	s_mov_b32 m0, s21
	ds_read_b128 v[148:151], v138
	ds_read_b128 v[226:229], v138 offset:1024
	ds_read_b128 v[230:233], v138 offset:2048
	ds_read_b128 v[234:237], v138 offset:3072
	global_load_lds_dwordx4 v[238:239], off
	v_lshl_add_u64 v[238:239], v[244:245], 0, s[44:45]
	s_add_i32 m0, s21, 0x2000
	s_nop 0
	global_load_lds_dwordx4 v[238:239], off
	s_barrier
; #define PG8_STAGE(bufoff, gbase, v0, v1) do { \
;         __builtin_amdgcn_global_load_lds((const unsigned*)((const char*)(gbase) + (v0)), (LAS unsigned*)(lds + (bufoff) + ldsw), 16, 0, 0); \
;         __builtin_amdgcn_global_load_lds((const unsigned*)((const char*)(gbase) + (v1)), (LAS unsigned*)(lds + (bufoff) + ldsw + 8192), 16, 0, 0); } while (0)
; #define PG8_LDA(dst, b, h) do { _Pragma("unroll") for (int m = 0; m < 4; ++m) _Pragma("unroll") for (int k = 0; k < 2; ++k) dst[m][k] = *(const LAS bf16x8*)(lds + PG8_SA(b, h) + aoff + m * 2048 + k * 1024); } while (0)
; #define PG8_MMA(ai, bj, At, Bt) do { __builtin_amdgcn_s_setprio(1); _Pragma("unroll") for (int m = 0; m < 4; ++m) _Pragma("unroll") for (int n = 0; n < 2; ++n) _Pragma("unroll") for (int k = 0; k < 2; ++k) \
;         acc[ai][bj][m][n] = __builtin_amdgcn_mfma_f32_16x16x32_bf16(Bt[n][k], At[m][k], acc[ai][bj][m][n], 0, 0, 0); __builtin_amdgcn_s_setprio(0); } while (0)
; #define PG8_WAIT_V(n) asm volatile("s_waitcnt vmcnt(" #n ")" ::: "memory")
; #define PG8_WAIT_L(n) asm volatile("s_waitcnt lgkmcnt(" #n ")" ::: "memory")
; #define PG8_BAR __builtin_amdgcn_s_barrier()
; #define PG8_SCHED __builtin_amdgcn_sched_barrier(0)
; template <class Epi, class Sched>
; __device__ __forceinline__ void gemm_phase(LAS unsigned char* lds, const Sched& S, const Epi& E) {
;     ...
;             const bool last = (t == nt - 2);
;             const char* a1 = cA + (size_t)(t + 1) * kstep;
;             const char* a2 = last ? nA : cA + (size_t)(t + 2) * kstep; const char* b2 = last ? nB : cB + (size_t)(t + 2) * kstep;
;             const char* a3 = a2 + kstep; const char* b3 = b2 + kstep;
;             const unsigned xA0 = last ? nvA0 : vA0, xA1 = last ? nvA1 : vA1, xB0 = last ? nvB0 : vB0, xB1 = last ? nvB1 : vB1;
;             const size_t xhA = last ? nhA : hA, xhB = last ? nhB : hB;
;     ...
;             PG8_BAR; PG8_WAIT_L(0); PG8_MMA(0, 1, At, B1); PG8_BAR;
;             PG8_LDA(At, 1, 1); PG8_STAGE(PG8_SA(1, 0), a3, xA0, xA1);
;             PG8_BAR; PG8_WAIT_L(0); PG8_MMA(1, 0, At, B0); PG8_BAR; PG8_SCHED;
;             PG8_STAGE(PG8_SB(1, 1), b3 + xhB, xB0, xB1);
;             PG8_WAIT_V(6); PG8_BAR; PG8_MMA(1, 1, At, B1); PG8_BAR;
	s_waitcnt lgkmcnt(0)
	s_setprio 1
	s_waitcnt lgkmcnt(0)
	v_mfma_f32_16x16x32_bf16 v[108:111], v[148:151], v[194:197], v[108:111]
	v_mfma_f32_16x16x32_bf16 v[104:107], v[230:233], v[194:197], v[104:107]
	v_mfma_f32_16x16x32_bf16 v[92:95], v[148:151], v[202:205], v[92:95]
	v_mfma_f32_16x16x32_bf16 v[88:91], v[230:233], v[202:205], v[88:91]
	v_mfma_f32_16x16x32_bf16 v[76:79], v[148:151], v[210:213], v[76:79]
	v_mfma_f32_16x16x32_bf16 v[72:75], v[230:233], v[210:213], v[72:75]
	v_mfma_f32_16x16x32_bf16 v[68:71], v[148:151], v[218:221], v[68:71]
	v_mfma_f32_16x16x32_bf16 v[64:67], v[230:233], v[218:221], v[64:67]
	v_mfma_f32_16x16x32_bf16 v[108:111], v[226:229], v[198:201], v[108:111]
	v_mfma_f32_16x16x32_bf16 v[104:107], v[234:237], v[198:201], v[104:107]
	v_mfma_f32_16x16x32_bf16 v[92:95], v[226:229], v[206:209], v[92:95]
	v_mfma_f32_16x16x32_bf16 v[88:91], v[234:237], v[206:209], v[88:91]
	v_mfma_f32_16x16x32_bf16 v[76:79], v[226:229], v[214:217], v[76:79]
	v_mfma_f32_16x16x32_bf16 v[72:75], v[234:237], v[214:217], v[72:75]
	v_mfma_f32_16x16x32_bf16 v[68:71], v[226:229], v[222:225], v[68:71]
	v_mfma_f32_16x16x32_bf16 v[64:67], v[234:237], v[222:225], v[64:67]
	s_setprio 0
	s_mov_b32 m0, s64
	v_lshl_add_u64 v[238:239], v[246:247], 0, s[44:45]
	s_barrier
	ds_read_b128 v[194:197], v154 offset:49152
	ds_read_b128 v[198:201], v154 offset:50176
	ds_read_b128 v[202:205], v154 offset:51200
	ds_read_b128 v[206:209], v154 offset:52224
	ds_read_b128 v[210:213], v154 offset:53248
	ds_read_b128 v[214:217], v154 offset:54272
	ds_read_b128 v[218:221], v154 offset:55296
	ds_read_b128 v[222:225], v154 offset:56320
	global_load_lds_dwordx4 v[238:239], off
	v_lshl_add_u64 v[238:239], v[248:249], 0, s[44:45]
	s_mov_b32 m0, s65
	s_nop 0
	global_load_lds_dwordx4 v[238:239], off
	s_barrier
	s_waitcnt lgkmcnt(0)
	s_setprio 1
	s_waitcnt lgkmcnt(0)
	v_mfma_f32_16x16x32_bf16 v[60:63], v[158:161], v[194:197], v[60:63]
	v_mfma_f32_16x16x32_bf16 v[56:59], v[186:189], v[194:197], v[56:59]
	v_mfma_f32_16x16x32_bf16 v[52:55], v[158:161], v[202:205], v[52:55]
	v_mfma_f32_16x16x32_bf16 v[44:47], v[186:189], v[202:205], v[44:47]
	v_mfma_f32_16x16x32_bf16 v[36:39], v[158:161], v[210:213], v[36:39]
	v_mfma_f32_16x16x32_bf16 v[28:31], v[186:189], v[210:213], v[28:31]
	v_mfma_f32_16x16x32_bf16 v[20:23], v[158:161], v[218:221], v[20:23]
	v_mfma_f32_16x16x32_bf16 v[12:15], v[186:189], v[218:221], v[12:15]
	v_mfma_f32_16x16x32_bf16 v[60:63], v[182:185], v[198:201], v[60:63]
	v_mfma_f32_16x16x32_bf16 v[56:59], v[190:193], v[198:201], v[56:59]
	v_mfma_f32_16x16x32_bf16 v[52:55], v[182:185], v[206:209], v[52:55]
	v_mfma_f32_16x16x32_bf16 v[44:47], v[190:193], v[206:209], v[44:47]
	v_mfma_f32_16x16x32_bf16 v[36:39], v[182:185], v[214:217], v[36:39]
	v_mfma_f32_16x16x32_bf16 v[28:31], v[190:193], v[214:217], v[28:31]
	v_mfma_f32_16x16x32_bf16 v[20:23], v[182:185], v[222:225], v[20:23]
	v_mfma_f32_16x16x32_bf16 v[12:15], v[190:193], v[222:225], v[12:15]
	s_setprio 0
	s_barrier
	s_add_u32 s38, s38, 0x80080
	s_addc_u32 s39, s39, 0
	s_add_i32 s21, s40, s43
	s_mov_b32 m0, s21
	s_nop 0
	global_load_lds_dwordx4 v136, s[38:39]
	s_add_i32 m0, s21, 0x2000
	s_nop 0
	global_load_lds_dwordx4 v146, s[38:39]
	s_waitcnt vmcnt(6)
	s_barrier
	s_setprio 1
	v_mfma_f32_16x16x32_bf16 v[48:51], v[148:151], v[194:197], v[48:51]
	v_mfma_f32_16x16x32_bf16 v[40:43], v[230:233], v[194:197], v[40:43]
	v_mfma_f32_16x16x32_bf16 v[32:35], v[148:151], v[202:205], v[32:35]
	v_mfma_f32_16x16x32_bf16 v[24:27], v[230:233], v[202:205], v[24:27]
	v_mfma_f32_16x16x32_bf16 v[16:19], v[148:151], v[210:213], v[16:19]
	v_mfma_f32_16x16x32_bf16 v[8:11], v[230:233], v[210:213], v[8:11]
	v_mfma_f32_16x16x32_bf16 v[4:7], v[148:151], v[218:221], v[4:7]
	v_mfma_f32_16x16x32_bf16 v[0:3], v[230:233], v[218:221], v[0:3]
	v_mfma_f32_16x16x32_bf16 v[48:51], v[226:229], v[198:201], v[48:51]
	v_mfma_f32_16x16x32_bf16 v[40:43], v[234:237], v[198:201], v[40:43]
	v_mfma_f32_16x16x32_bf16 v[32:35], v[226:229], v[206:209], v[32:35]
	v_mfma_f32_16x16x32_bf16 v[24:27], v[234:237], v[206:209], v[24:27]
	v_mfma_f32_16x16x32_bf16 v[16:19], v[226:229], v[214:217], v[16:19]
	v_mfma_f32_16x16x32_bf16 v[8:11], v[234:237], v[214:217], v[8:11]
	v_mfma_f32_16x16x32_bf16 v[4:7], v[226:229], v[222:225], v[4:7]
	v_mfma_f32_16x16x32_bf16 v[0:3], v[234:237], v[222:225], v[0:3]
	s_setprio 0
	s_add_i32 s15, s15, 2
	s_add_u32 s26, s26, 0x100
	s_addc_u32 s27, s27, 0
	s_add_u32 s34, s34, 0x100
	s_addc_u32 s35, s35, 0
	s_cmp_gt_u32 s15, 29
	s_cbranch_scc1 .Lrot_exit_0
	s_cmp_eq_u32 s15, 28
	s_cselect_b64 s[40:41], -1, 0
	s_and_b64 vcc, exec, s[40:41]
	v_mov_b64_e32 v[148:149], v[130:131]
	v_mov_b64_e32 v[150:151], v[128:129]
	v_mov_b32_e32 v146, v156
	v_mov_b32_e32 v136, v155
	s_mov_b64 s[38:39], s[24:25]
	s_cbranch_vccnz .Lrot_join_0
	v_mov_b64_e32 v[148:149], v[134:135]
	v_mov_b64_e32 v[150:151], v[132:133]
	v_mov_b32_e32 v146, v142
	v_mov_b32_e32 v136, v144
	s_mov_b64 s[38:39], s[34:35]
.Lrot_join_0:
	s_barrier
	s_branch .LBB0_306

; #define PG8_STAGE(bufoff, gbase, v0, v1) do { \
;         __builtin_amdgcn_global_load_lds((const unsigned*)((const char*)(gbase) + (v0)), (LAS unsigned*)(lds + (bufoff) + ldsw), 16, 0, 0); \
;         __builtin_amdgcn_global_load_lds((const unsigned*)((const char*)(gbase) + (v1)), (LAS unsigned*)(lds + (bufoff) + ldsw + 8192), 16, 0, 0); } while (0)
; #define PG8_LDA(dst, b, h) do { _Pragma("unroll") for (int m = 0; m < 4; ++m) _Pragma("unroll") for (int k = 0; k < 2; ++k) dst[m][k] = *(const LAS bf16x8*)(lds + PG8_SA(b, h) + aoff + m * 2048 + k * 1024); } while (0)
; #define PG8_LDB(dst, b, h) do { _Pragma("unroll") for (int n = 0; n < 2; ++n) _Pragma("unroll") for (int k = 0; k < 2; ++k) dst[n][k] = *(const LAS bf16x8*)(lds + PG8_SB(b, h) + boff + n * 2048 + k * 1024); } while (0)
; #define PG8_MMA(ai, bj, At, Bt) do { __builtin_amdgcn_s_setprio(1); _Pragma("unroll") for (int m = 0; m < 4; ++m) _Pragma("unroll") for (int n = 0; n < 2; ++n) _Pragma("unroll") for (int k = 0; k < 2; ++k) \
;         acc[ai][bj][m][n] = __builtin_amdgcn_mfma_f32_16x16x32_bf16(Bt[n][k], At[m][k], acc[ai][bj][m][n], 0, 0, 0); __builtin_amdgcn_s_setprio(0); } while (0)
; #define PG8_WAIT_L(n) asm volatile("s_waitcnt lgkmcnt(" #n ")" ::: "memory")
; template <class Epi, class Sched>
; __device__ __forceinline__ void gemm_phase(LAS unsigned char* lds, const Sched& S, const Epi& E) {
;     ...
;             const bool last = (t == nt - 2);
;             const char* a1 = cA + (size_t)(t + 1) * kstep;
;             const char* a2 = last ? nA : cA + (size_t)(t + 2) * kstep; const char* b2 = last ? nB : cB + (size_t)(t + 2) * kstep;
;             const char* a3 = a2 + kstep; const char* b3 = b2 + kstep;
;             const unsigned xA0 = last ? nvA0 : vA0, xA1 = last ? nvA1 : vA1, xB0 = last ? nvB0 : vB0, xB1 = last ? nvB1 : vB1;
;             const size_t xhA = last ? nhA : hA, xhB = last ? nhB : hB;
;             PG8_LDB(B0, 0, 0); PG8_SCHED; PG8_LDA(At, 0, 0); PG8_STAGE(PG8_SA(1, 1), a1 + hA, vA0, vA1);
;             PG8_WAIT_L(8); PG8_BAR; PG8_WAIT_L(0); PG8_MMA(0, 0, At, B0); PG8_BAR; PG8_SCHED;
;             PG8_LDB(B1, 0, 1); PG8_STAGE(PG8_SB(0, 0), b2, xB0, xB1);
;             PG8_BAR; PG8_WAIT_L(0); PG8_MMA(0, 1, At, B1); PG8_BAR;
;             PG8_LDA(At, 0, 1); PG8_STAGE(PG8_SA(0, 0), a2, xA0, xA1);
;             PG8_BAR; PG8_WAIT_L(0); PG8_MMA(1, 0, At, B0); PG8_BAR; PG8_SCHED;
.LBB0_574:
	s_add_i32 s49, s49, 2
	s_add_u32 s65, s34, 0x80
	s_addc_u32 vcc_lo, s35, 0
	s_and_b64 s[54:55], exec, s[54:55]
	s_cselect_b32 s55, s41, vcc_lo
	s_cselect_b32 s54, s40, s65
	s_add_i32 s65, 0, 0x10000
	v_add_u32_e32 v138, s65, v184
	ds_read_b128 v[158:161], v138
	ds_read_b128 v[186:189], v138 offset:1024
	ds_read_b128 v[190:193], v138 offset:2048
	ds_read_b128 v[194:197], v138 offset:3072
	v_lshl_add_u64 v[230:231], s[34:35], 0, v[134:135]
	s_add_i32 m0, s91, 0xc000
	ds_read_b128 v[198:201], v185
	ds_read_b128 v[202:205], v185 offset:1024
	ds_read_b128 v[206:209], v185 offset:2048
	ds_read_b128 v[210:213], v185 offset:3072
	ds_read_b128 v[214:217], v185 offset:4096
	ds_read_b128 v[218:221], v185 offset:5120
	ds_read_b128 v[222:225], v185 offset:6144
	ds_read_b128 v[226:229], v185 offset:7168
	global_load_lds_dwordx4 v[230:231], off
	v_lshl_add_u64 v[230:231], s[34:35], 0, v[150:151]
	s_add_i32 m0, s91, 0xe000
	s_nop 0
	global_load_lds_dwordx4 v[230:231], off
	s_waitcnt lgkmcnt(8)
	s_barrier
	s_waitcnt lgkmcnt(0)
	s_setprio 1
	s_waitcnt lgkmcnt(0)
	v_mfma_f32_16x16x32_bf16 v[124:127], v[158:161], v[198:201], v[124:127]
	v_mfma_f32_16x16x32_bf16 v[120:123], v[190:193], v[198:201], v[120:123]
	v_mfma_f32_16x16x32_bf16 v[116:119], v[158:161], v[206:209], v[116:119]
	v_mfma_f32_16x16x32_bf16 v[112:115], v[190:193], v[206:209], v[112:115]
	v_mfma_f32_16x16x32_bf16 v[108:111], v[158:161], v[214:217], v[108:111]
	v_mfma_f32_16x16x32_bf16 v[104:107], v[190:193], v[214:217], v[104:107]
	v_mfma_f32_16x16x32_bf16 v[100:103], v[158:161], v[222:225], v[100:103]
	v_mfma_f32_16x16x32_bf16 v[96:99], v[190:193], v[222:225], v[96:99]
	v_mfma_f32_16x16x32_bf16 v[124:127], v[186:189], v[202:205], v[124:127]
	v_mfma_f32_16x16x32_bf16 v[120:123], v[194:197], v[202:205], v[120:123]
	v_mfma_f32_16x16x32_bf16 v[116:119], v[186:189], v[210:213], v[116:119]
	v_mfma_f32_16x16x32_bf16 v[112:115], v[194:197], v[210:213], v[112:115]
	v_mfma_f32_16x16x32_bf16 v[108:111], v[186:189], v[218:221], v[108:111]
	v_mfma_f32_16x16x32_bf16 v[104:107], v[194:197], v[218:221], v[104:107]
	v_mfma_f32_16x16x32_bf16 v[100:103], v[186:189], v[226:229], v[100:103]
	v_mfma_f32_16x16x32_bf16 v[96:99], v[194:197], v[226:229], v[96:99]
	s_setprio 0
	s_barrier
	s_add_i32 vcc_lo, 0, 0x14000
	s_add_i32 s65, s65, s9
	v_add_u32_e32 v138, vcc_lo, v184
	s_mov_b32 m0, s65
	ds_read_b128 v[230:233], v138
	ds_read_b128 v[234:237], v138 offset:1024
	ds_read_b128 v[238:241], v138 offset:2048
	ds_read_b128 v[242:245], v138 offset:3072
	global_load_lds_dwordx4 v136, s[92:93]
	s_add_i32 m0, s65, 0x2000
	v_mov_b32_e32 v157, v137
	global_load_lds_dwordx4 v156, s[92:93]
	s_barrier
	s_waitcnt lgkmcnt(0)
	v_lshl_add_u64 v[246:247], s[92:93], 0, v[136:137]
	v_lshl_add_u64 v[248:249], s[92:93], 0, v[156:157]
	s_setprio 1
	s_waitcnt lgkmcnt(0)
	v_mfma_f32_16x16x32_bf16 v[92:95], v[230:233], v[198:201], v[92:95]
	v_mfma_f32_16x16x32_bf16 v[88:91], v[238:241], v[198:201], v[88:91]
	v_mfma_f32_16x16x32_bf16 v[84:87], v[230:233], v[206:209], v[84:87]
	v_mfma_f32_16x16x32_bf16 v[80:83], v[238:241], v[206:209], v[80:83]
	v_mfma_f32_16x16x32_bf16 v[76:79], v[230:233], v[214:217], v[76:79]
	v_mfma_f32_16x16x32_bf16 v[72:75], v[238:241], v[214:217], v[72:75]
	v_mfma_f32_16x16x32_bf16 v[68:71], v[230:233], v[222:225], v[68:71]
	v_mfma_f32_16x16x32_bf16 v[64:67], v[238:241], v[222:225], v[64:67]
	v_mfma_f32_16x16x32_bf16 v[92:95], v[234:237], v[202:205], v[92:95]
	v_mfma_f32_16x16x32_bf16 v[88:91], v[242:245], v[202:205], v[88:91]
	v_mfma_f32_16x16x32_bf16 v[84:87], v[234:237], v[210:213], v[84:87]
	v_mfma_f32_16x16x32_bf16 v[80:83], v[242:245], v[210:213], v[80:83]
	v_mfma_f32_16x16x32_bf16 v[76:79], v[234:237], v[218:221], v[76:79]
	v_mfma_f32_16x16x32_bf16 v[72:75], v[242:245], v[218:221], v[72:75]
	v_mfma_f32_16x16x32_bf16 v[68:71], v[234:237], v[226:229], v[68:71]
	v_mfma_f32_16x16x32_bf16 v[64:67], v[242:245], v[226:229], v[64:67]
	s_setprio 0
	s_mov_b32 m0, s91
	v_lshl_add_u64 v[250:251], s[54:55], 0, v[154:155]
	s_barrier
	ds_read_b128 v[198:201], v185 offset:16384
	ds_read_b128 v[202:205], v185 offset:17408
	ds_read_b128 v[206:209], v185 offset:18432
	ds_read_b128 v[210:213], v185 offset:19456
	ds_read_b128 v[214:217], v185 offset:20480
	ds_read_b128 v[218:221], v185 offset:21504
	ds_read_b128 v[222:225], v185 offset:22528
	ds_read_b128 v[226:229], v185 offset:23552
	global_load_lds_dwordx4 v[250:251], off
	v_lshl_add_u64 v[140:141], s[54:55], 0, v[152:153]
	s_mov_b32 m0, s50
	s_nop 0
	global_load_lds_dwordx4 v[140:141], off
	s_barrier
	s_waitcnt lgkmcnt(0)
	s_setprio 1
	s_waitcnt lgkmcnt(0)
	v_mfma_f32_16x16x32_bf16 v[60:63], v[158:161], v[198:201], v[60:63]
	v_mfma_f32_16x16x32_bf16 v[56:59], v[190:193], v[198:201], v[56:59]
	v_mfma_f32_16x16x32_bf16 v[52:55], v[158:161], v[206:209], v[52:55]
	v_mfma_f32_16x16x32_bf16 v[48:51], v[190:193], v[206:209], v[48:51]
	v_mfma_f32_16x16x32_bf16 v[44:47], v[158:161], v[214:217], v[44:47]
	v_mfma_f32_16x16x32_bf16 v[40:43], v[190:193], v[214:217], v[40:43]
	v_mfma_f32_16x16x32_bf16 v[36:39], v[158:161], v[222:225], v[36:39]
	v_mfma_f32_16x16x32_bf16 v[32:35], v[190:193], v[222:225], v[32:35]
	v_mfma_f32_16x16x32_bf16 v[60:63], v[186:189], v[202:205], v[60:63]
	v_mfma_f32_16x16x32_bf16 v[56:59], v[194:197], v[202:205], v[56:59]
	v_mfma_f32_16x16x32_bf16 v[52:55], v[186:189], v[210:213], v[52:55]
	v_mfma_f32_16x16x32_bf16 v[48:51], v[194:197], v[210:213], v[48:51]
	v_mfma_f32_16x16x32_bf16 v[44:47], v[186:189], v[218:221], v[44:47]
	v_mfma_f32_16x16x32_bf16 v[40:43], v[194:197], v[218:221], v[40:43]
	v_mfma_f32_16x16x32_bf16 v[36:39], v[186:189], v[226:229], v[36:39]
	v_mfma_f32_16x16x32_bf16 v[32:35], v[194:197], v[226:229], v[32:35]
	s_setprio 0
	s_barrier
; #define PG8_STAGE(bufoff, gbase, v0, v1) do { \
;         __builtin_amdgcn_global_load_lds((const unsigned*)((const char*)(gbase) + (v0)), (LAS unsigned*)(lds + (bufoff) + ldsw), 16, 0, 0); \
;         __builtin_amdgcn_global_load_lds((const unsigned*)((const char*)(gbase) + (v1)), (LAS unsigned*)(lds + (bufoff) + ldsw + 8192), 16, 0, 0); } while (0)
; #define PG8_LDA(dst, b, h) do { _Pragma("unroll") for (int m = 0; m < 4; ++m) _Pragma("unroll") for (int k = 0; k < 2; ++k) dst[m][k] = *(const LAS bf16x8*)(lds + PG8_SA(b, h) + aoff + m * 2048 + k * 1024); } while (0)
; #define PG8_LDB(dst, b, h) do { _Pragma("unroll") for (int n = 0; n < 2; ++n) _Pragma("unroll") for (int k = 0; k < 2; ++k) dst[n][k] = *(const LAS bf16x8*)(lds + PG8_SB(b, h) + boff + n * 2048 + k * 1024); } while (0)
; #define PG8_MMA(ai, bj, At, Bt) do { __builtin_amdgcn_s_setprio(1); _Pragma("unroll") for (int m = 0; m < 4; ++m) _Pragma("unroll") for (int n = 0; n < 2; ++n) _Pragma("unroll") for (int k = 0; k < 2; ++k) \
;         acc[ai][bj][m][n] = __builtin_amdgcn_mfma_f32_16x16x32_bf16(Bt[n][k], At[m][k], acc[ai][bj][m][n], 0, 0, 0); __builtin_amdgcn_s_setprio(0); } while (0)
; #define PG8_WAIT_V(n) asm volatile("s_waitcnt vmcnt(" #n ")" ::: "memory")
; #define PG8_WAIT_L(n) asm volatile("s_waitcnt lgkmcnt(" #n ")" ::: "memory")
; #define PG8_BAR __builtin_amdgcn_s_barrier()
; #define PG8_SCHED __builtin_amdgcn_sched_barrier(0)
; template <class Epi, class Sched>
; __device__ __forceinline__ void gemm_phase(LAS unsigned char* lds, const Sched& S, const Epi& E) {
;     ...
;             PG8_STAGE(PG8_SB(0, 1), b2 + xhB, xB0, xB1);
;             PG8_WAIT_V(6); PG8_BAR; PG8_MMA(1, 1, At, B1); PG8_BAR;
;             PG8_LDB(B0, 1, 0); PG8_SCHED; PG8_LDA(At, 1, 0); PG8_STAGE(PG8_SA(0, 1), a2 + xhA, xA0, xA1);
;             PG8_WAIT_L(8); PG8_BAR; PG8_WAIT_L(0); PG8_MMA(0, 0, At, B0); PG8_BAR; PG8_SCHED;
;             PG8_LDB(B1, 1, 1); PG8_STAGE(PG8_SB(1, 0), b3, xB0, xB1);
	s_add_u32 s88, s92, s88
	s_addc_u32 s89, s93, s89
	s_add_i32 s65, vcc_lo, s9
	s_mov_b32 m0, s65
	v_lshl_add_u64 v[160:161], s[88:89], 0, v[136:137]
	global_load_lds_dwordx4 v136, s[88:89]
	s_add_i32 m0, s65, 0x2000
	v_lshl_add_u64 v[138:139], s[88:89], 0, v[156:157]
	global_load_lds_dwordx4 v156, s[88:89]
	s_waitcnt vmcnt(6)
	s_barrier
	s_setprio 1
	v_mfma_f32_16x16x32_bf16 v[28:31], v[230:233], v[198:201], v[28:31]
	v_mfma_f32_16x16x32_bf16 v[24:27], v[238:241], v[198:201], v[24:27]
	v_mfma_f32_16x16x32_bf16 v[20:23], v[230:233], v[206:209], v[20:23]
	v_mfma_f32_16x16x32_bf16 v[16:19], v[238:241], v[206:209], v[16:19]
	v_mfma_f32_16x16x32_bf16 v[12:15], v[230:233], v[214:217], v[12:15]
	v_mfma_f32_16x16x32_bf16 v[8:11], v[238:241], v[214:217], v[8:11]
	v_mfma_f32_16x16x32_bf16 v[4:7], v[230:233], v[222:225], v[4:7]
	v_mfma_f32_16x16x32_bf16 v[0:3], v[238:241], v[222:225], v[0:3]
	v_mfma_f32_16x16x32_bf16 v[28:31], v[234:237], v[202:205], v[28:31]
	v_mfma_f32_16x16x32_bf16 v[24:27], v[242:245], v[202:205], v[24:27]
	v_mfma_f32_16x16x32_bf16 v[20:23], v[234:237], v[210:213], v[20:23]
	v_mfma_f32_16x16x32_bf16 v[16:19], v[242:245], v[210:213], v[16:19]
	v_mfma_f32_16x16x32_bf16 v[12:15], v[234:237], v[218:221], v[12:15]
	v_mfma_f32_16x16x32_bf16 v[8:11], v[242:245], v[218:221], v[8:11]
	v_mfma_f32_16x16x32_bf16 v[4:7], v[234:237], v[226:229], v[4:7]
	v_mfma_f32_16x16x32_bf16 v[0:3], v[242:245], v[226:229], v[0:3]
	s_setprio 0
	s_add_i32 s65, 0, 0x18000
	v_add_u32_e32 v136, s65, v184
	s_barrier
	ds_read_b128 v[156:159], v136
	ds_read_b128 v[186:189], v136 offset:1024
	ds_read_b128 v[190:193], v136 offset:2048
	ds_read_b128 v[194:197], v136 offset:3072
	s_add_u32 s54, s54, s82
	s_addc_u32 s55, s55, s83
	s_mov_b32 m0, s51
	v_lshl_add_u64 v[154:155], s[54:55], 0, v[154:155]
	ds_read_b128 v[198:201], v185 offset:32768
	ds_read_b128 v[202:205], v185 offset:33792
	ds_read_b128 v[206:209], v185 offset:34816
	ds_read_b128 v[210:213], v185 offset:35840
	ds_read_b128 v[214:217], v185 offset:36864
	ds_read_b128 v[218:221], v185 offset:37888
	ds_read_b128 v[222:225], v185 offset:38912
	ds_read_b128 v[226:229], v185 offset:39936
	global_load_lds_dwordx4 v[154:155], off
	v_lshl_add_u64 v[152:153], s[54:55], 0, v[152:153]
	s_mov_b32 m0, s8
	s_nop 0
	global_load_lds_dwordx4 v[152:153], off
	s_waitcnt lgkmcnt(8)
	s_barrier
	s_waitcnt lgkmcnt(0)
	s_setprio 1
	s_waitcnt lgkmcnt(0)
	v_mfma_f32_16x16x32_bf16 v[124:127], v[156:159], v[198:201], v[124:127]
	v_mfma_f32_16x16x32_bf16 v[120:123], v[190:193], v[198:201], v[120:123]
	v_mfma_f32_16x16x32_bf16 v[116:119], v[156:159], v[206:209], v[116:119]
	v_mfma_f32_16x16x32_bf16 v[112:115], v[190:193], v[206:209], v[112:115]
	v_mfma_f32_16x16x32_bf16 v[108:111], v[156:159], v[214:217], v[108:111]
	v_mfma_f32_16x16x32_bf16 v[104:107], v[190:193], v[214:217], v[104:107]
	v_mfma_f32_16x16x32_bf16 v[100:103], v[156:159], v[222:225], v[100:103]
	v_mfma_f32_16x16x32_bf16 v[96:99], v[190:193], v[222:225], v[96:99]
	v_mfma_f32_16x16x32_bf16 v[124:127], v[186:189], v[202:205], v[124:127]
	v_mfma_f32_16x16x32_bf16 v[120:123], v[194:197], v[202:205], v[120:123]
	v_mfma_f32_16x16x32_bf16 v[116:119], v[186:189], v[210:213], v[116:119]
	v_mfma_f32_16x16x32_bf16 v[112:115], v[194:197], v[210:213], v[112:115]
	v_mfma_f32_16x16x32_bf16 v[108:111], v[186:189], v[218:221], v[108:111]
	v_mfma_f32_16x16x32_bf16 v[104:107], v[194:197], v[218:221], v[104:107]
	v_mfma_f32_16x16x32_bf16 v[100:103], v[186:189], v[226:229], v[100:103]
	v_mfma_f32_16x16x32_bf16 v[96:99], v[194:197], v[226:229], v[96:99]
	s_setprio 0
	s_barrier
	s_add_i32 s54, 0, 0x1c000
	s_add_i32 s55, s65, s9
	v_add_u32_e32 v136, s54, v184
	v_lshl_add_u64 v[242:243], v[246:247], 0, s[44:45]
	s_mov_b32 m0, s55
	ds_read_b128 v[152:155], v136
	ds_read_b128 v[230:233], v136 offset:1024
	ds_read_b128 v[234:237], v136 offset:2048
	ds_read_b128 v[238:241], v136 offset:3072
	global_load_lds_dwordx4 v[242:243], off
	v_lshl_add_u64 v[242:243], v[248:249], 0, s[44:45]
	s_add_i32 m0, s55, 0x2000
	s_nop 0
	global_load_lds_dwordx4 v[242:243], off
	s_barrier
; #define PG8_STAGE(bufoff, gbase, v0, v1) do { \
;         __builtin_amdgcn_global_load_lds((const unsigned*)((const char*)(gbase) + (v0)), (LAS unsigned*)(lds + (bufoff) + ldsw), 16, 0, 0); \
;         __builtin_amdgcn_global_load_lds((const unsigned*)((const char*)(gbase) + (v1)), (LAS unsigned*)(lds + (bufoff) + ldsw + 8192), 16, 0, 0); } while (0)
; #define PG8_LDA(dst, b, h) do { _Pragma("unroll") for (int m = 0; m < 4; ++m) _Pragma("unroll") for (int k = 0; k < 2; ++k) dst[m][k] = *(const LAS bf16x8*)(lds + PG8_SA(b, h) + aoff + m * 2048 + k * 1024); } while (0)
; #define PG8_MMA(ai, bj, At, Bt) do { __builtin_amdgcn_s_setprio(1); _Pragma("unroll") for (int m = 0; m < 4; ++m) _Pragma("unroll") for (int n = 0; n < 2; ++n) _Pragma("unroll") for (int k = 0; k < 2; ++k) \
;         acc[ai][bj][m][n] = __builtin_amdgcn_mfma_f32_16x16x32_bf16(Bt[n][k], At[m][k], acc[ai][bj][m][n], 0, 0, 0); __builtin_amdgcn_s_setprio(0); } while (0)
; #define PG8_WAIT_V(n) asm volatile("s_waitcnt vmcnt(" #n ")" ::: "memory")
; #define PG8_WAIT_L(n) asm volatile("s_waitcnt lgkmcnt(" #n ")" ::: "memory")
; #define PG8_BAR __builtin_amdgcn_s_barrier()
; #define PG8_SCHED __builtin_amdgcn_sched_barrier(0)
; template <class Epi, class Sched>
; __device__ __forceinline__ void gemm_phase(LAS unsigned char* lds, const Sched& S, const Epi& E) {
;     ...
;             const bool last = (t == nt - 2);
;             const char* a1 = cA + (size_t)(t + 1) * kstep;
;             const char* a2 = last ? nA : cA + (size_t)(t + 2) * kstep; const char* b2 = last ? nB : cB + (size_t)(t + 2) * kstep;
;             const char* a3 = a2 + kstep; const char* b3 = b2 + kstep;
;             const unsigned xA0 = last ? nvA0 : vA0, xA1 = last ? nvA1 : vA1, xB0 = last ? nvB0 : vB0, xB1 = last ? nvB1 : vB1;
;             const size_t xhA = last ? nhA : hA, xhB = last ? nhB : hB;
;     ...
;             PG8_BAR; PG8_WAIT_L(0); PG8_MMA(0, 1, At, B1); PG8_BAR;
;             PG8_LDA(At, 1, 1); PG8_STAGE(PG8_SA(1, 0), a3, xA0, xA1);
;             PG8_BAR; PG8_WAIT_L(0); PG8_MMA(1, 0, At, B0); PG8_BAR; PG8_SCHED;
;             PG8_STAGE(PG8_SB(1, 1), b3 + xhB, xB0, xB1);
;             PG8_WAIT_V(6); PG8_BAR; PG8_MMA(1, 1, At, B1); PG8_BAR;
	s_waitcnt lgkmcnt(0)
	s_setprio 1
	s_waitcnt lgkmcnt(0)
	v_mfma_f32_16x16x32_bf16 v[92:95], v[152:155], v[198:201], v[92:95]
	v_mfma_f32_16x16x32_bf16 v[88:91], v[234:237], v[198:201], v[88:91]
	v_mfma_f32_16x16x32_bf16 v[84:87], v[152:155], v[206:209], v[84:87]
	v_mfma_f32_16x16x32_bf16 v[80:83], v[234:237], v[206:209], v[80:83]
	v_mfma_f32_16x16x32_bf16 v[76:79], v[152:155], v[214:217], v[76:79]
	v_mfma_f32_16x16x32_bf16 v[72:75], v[234:237], v[214:217], v[72:75]
	v_mfma_f32_16x16x32_bf16 v[68:71], v[152:155], v[222:225], v[68:71]
	v_mfma_f32_16x16x32_bf16 v[64:67], v[234:237], v[222:225], v[64:67]
	v_mfma_f32_16x16x32_bf16 v[92:95], v[230:233], v[202:205], v[92:95]
	v_mfma_f32_16x16x32_bf16 v[88:91], v[238:241], v[202:205], v[88:91]
	v_mfma_f32_16x16x32_bf16 v[84:87], v[230:233], v[210:213], v[84:87]
	v_mfma_f32_16x16x32_bf16 v[80:83], v[238:241], v[210:213], v[80:83]
	v_mfma_f32_16x16x32_bf16 v[76:79], v[230:233], v[218:221], v[76:79]
	v_mfma_f32_16x16x32_bf16 v[72:75], v[238:241], v[218:221], v[72:75]
	v_mfma_f32_16x16x32_bf16 v[68:71], v[230:233], v[226:229], v[68:71]
	v_mfma_f32_16x16x32_bf16 v[64:67], v[238:241], v[226:229], v[64:67]
	s_setprio 0
	s_mov_b32 m0, s21
	v_lshl_add_u64 v[242:243], v[250:251], 0, s[44:45]
	s_barrier
	ds_read_b128 v[198:201], v185 offset:49152
	ds_read_b128 v[202:205], v185 offset:50176
	ds_read_b128 v[206:209], v185 offset:51200
	ds_read_b128 v[210:213], v185 offset:52224
	ds_read_b128 v[214:217], v185 offset:53248
	ds_read_b128 v[218:221], v185 offset:54272
	ds_read_b128 v[222:225], v185 offset:55296
	ds_read_b128 v[226:229], v185 offset:56320
	global_load_lds_dwordx4 v[242:243], off
	v_lshl_add_u64 v[140:141], v[140:141], 0, s[44:45]
	s_mov_b32 m0, s24
	s_nop 0
	global_load_lds_dwordx4 v[140:141], off
	s_barrier
	s_waitcnt lgkmcnt(0)
	s_setprio 1
	s_waitcnt lgkmcnt(0)
	v_mfma_f32_16x16x32_bf16 v[60:63], v[156:159], v[198:201], v[60:63]
	v_mfma_f32_16x16x32_bf16 v[56:59], v[190:193], v[198:201], v[56:59]
	v_mfma_f32_16x16x32_bf16 v[52:55], v[156:159], v[206:209], v[52:55]
	v_mfma_f32_16x16x32_bf16 v[48:51], v[190:193], v[206:209], v[48:51]
	v_mfma_f32_16x16x32_bf16 v[44:47], v[156:159], v[214:217], v[44:47]
	v_mfma_f32_16x16x32_bf16 v[40:43], v[190:193], v[214:217], v[40:43]
	v_mfma_f32_16x16x32_bf16 v[36:39], v[156:159], v[222:225], v[36:39]
	v_mfma_f32_16x16x32_bf16 v[32:35], v[190:193], v[222:225], v[32:35]
	v_mfma_f32_16x16x32_bf16 v[60:63], v[186:189], v[202:205], v[60:63]
	v_mfma_f32_16x16x32_bf16 v[56:59], v[194:197], v[202:205], v[56:59]
	v_mfma_f32_16x16x32_bf16 v[52:55], v[186:189], v[210:213], v[52:55]
	v_mfma_f32_16x16x32_bf16 v[48:51], v[194:197], v[210:213], v[48:51]
	v_mfma_f32_16x16x32_bf16 v[44:47], v[186:189], v[218:221], v[44:47]
	v_mfma_f32_16x16x32_bf16 v[40:43], v[194:197], v[218:221], v[40:43]
	v_mfma_f32_16x16x32_bf16 v[36:39], v[186:189], v[226:229], v[36:39]
	v_mfma_f32_16x16x32_bf16 v[32:35], v[194:197], v[226:229], v[32:35]
	s_setprio 0
	s_barrier
	s_add_i32 s54, s54, s9
	v_lshl_add_u64 v[140:141], v[160:161], 0, s[44:45]
	s_mov_b32 m0, s54
	v_lshl_add_u64 v[138:139], v[138:139], 0, s[44:45]
	global_load_lds_dwordx4 v[140:141], off
	s_add_i32 m0, s54, 0x2000
	s_nop 0
	global_load_lds_dwordx4 v[138:139], off
	s_waitcnt vmcnt(6)
	s_barrier
	s_setprio 1
	v_mfma_f32_16x16x32_bf16 v[28:31], v[152:155], v[198:201], v[28:31]
	v_mfma_f32_16x16x32_bf16 v[24:27], v[234:237], v[198:201], v[24:27]
	v_mfma_f32_16x16x32_bf16 v[20:23], v[152:155], v[206:209], v[20:23]
	v_mfma_f32_16x16x32_bf16 v[16:19], v[234:237], v[206:209], v[16:19]
	v_mfma_f32_16x16x32_bf16 v[12:15], v[152:155], v[214:217], v[12:15]
	v_mfma_f32_16x16x32_bf16 v[8:11], v[234:237], v[214:217], v[8:11]
	v_mfma_f32_16x16x32_bf16 v[4:7], v[152:155], v[222:225], v[4:7]
	v_mfma_f32_16x16x32_bf16 v[0:3], v[234:237], v[222:225], v[0:3]
	v_mfma_f32_16x16x32_bf16 v[28:31], v[230:233], v[202:205], v[28:31]
	v_mfma_f32_16x16x32_bf16 v[24:27], v[238:241], v[202:205], v[24:27]
	v_mfma_f32_16x16x32_bf16 v[20:23], v[230:233], v[210:213], v[20:23]
	v_mfma_f32_16x16x32_bf16 v[16:19], v[238:241], v[210:213], v[16:19]
	v_mfma_f32_16x16x32_bf16 v[12:15], v[230:233], v[218:221], v[12:15]
	v_mfma_f32_16x16x32_bf16 v[8:11], v[238:241], v[218:221], v[8:11]
	v_mfma_f32_16x16x32_bf16 v[4:7], v[230:233], v[226:229], v[4:7]
	v_mfma_f32_16x16x32_bf16 v[0:3], v[238:241], v[226:229], v[0:3]
	s_setprio 0
	s_add_u32 s34, s34, 0x100
	s_addc_u32 s35, s35, 0
	s_add_u32 s70, s70, 0x100
	s_addc_u32 s71, s71, 0
	s_cmp_ge_i32 s49, s36
	s_cbranch_scc1 .Lrot_exit_1
	s_cmp_eq_u32 s39, s49
	s_cselect_b64 s[54:55], -1, 0
	s_and_b64 vcc, exec, s[54:55]
	v_mov_b64_e32 v[152:153], v[144:145]
	v_mov_b64_e32 v[154:155], v[142:143]
	s_mov_b64 s[88:89], s[68:69]
	s_mov_b64 s[82:83], s[66:67]
	v_mov_b32_e32 v156, v148
	v_mov_b32_e32 v136, v146
	s_mov_b64 s[92:93], s[42:43]
	s_cbranch_vccnz .Lrot_join_1
	v_mov_b64_e32 v[152:153], v[128:129]
	v_mov_b64_e32 v[154:155], v[132:133]
	s_mov_b64 s[88:89], s[12:13]
	s_mov_b64 s[82:83], s[14:15]
	v_mov_b32_e32 v156, v130
	v_mov_b32_e32 v136, v131
	s_mov_b64 s[92:93], s[70:71]

; #define PG8_STAGE(bufoff, gbase, v0, v1) do { \
;         __builtin_amdgcn_global_load_lds((const unsigned*)((const char*)(gbase) + (v0)), (LAS unsigned*)(lds + (bufoff) + ldsw), 16, 0, 0); \
;         __builtin_amdgcn_global_load_lds((const unsigned*)((const char*)(gbase) + (v1)), (LAS unsigned*)(lds + (bufoff) + ldsw + 8192), 16, 0, 0); } while (0)
; #define PG8_LDA(dst, b, h) do { _Pragma("unroll") for (int m = 0; m < 4; ++m) _Pragma("unroll") for (int k = 0; k < 2; ++k) dst[m][k] = *(const LAS bf16x8*)(lds + PG8_SA(b, h) + aoff + m * 2048 + k * 1024); } while (0)
; #define PG8_LDB(dst, b, h) do { _Pragma("unroll") for (int n = 0; n < 2; ++n) _Pragma("unroll") for (int k = 0; k < 2; ++k) dst[n][k] = *(const LAS bf16x8*)(lds + PG8_SB(b, h) + boff + n * 2048 + k * 1024); } while (0)
; #define PG8_MMA(ai, bj, At, Bt) do { __builtin_amdgcn_s_setprio(1); _Pragma("unroll") for (int m = 0; m < 4; ++m) _Pragma("unroll") for (int n = 0; n < 2; ++n) _Pragma("unroll") for (int k = 0; k < 2; ++k) \
;         acc[ai][bj][m][n] = __builtin_amdgcn_mfma_f32_16x16x32_bf16(Bt[n][k], At[m][k], acc[ai][bj][m][n], 0, 0, 0); __builtin_amdgcn_s_setprio(0); } while (0)
; #define PG8_WAIT_L(n) asm volatile("s_waitcnt lgkmcnt(" #n ")" ::: "memory")
; template <class Epi, class Sched>
; __device__ __forceinline__ void gemm_phase(LAS unsigned char* lds, const Sched& S, const Epi& E) {
;     ...
;             const bool last = (t == nt - 2);
;             const char* a1 = cA + (size_t)(t + 1) * kstep;
;             const char* a2 = last ? nA : cA + (size_t)(t + 2) * kstep; const char* b2 = last ? nB : cB + (size_t)(t + 2) * kstep;
;             const char* a3 = a2 + kstep; const char* b3 = b2 + kstep;
;             const unsigned xA0 = last ? nvA0 : vA0, xA1 = last ? nvA1 : vA1, xB0 = last ? nvB0 : vB0, xB1 = last ? nvB1 : vB1;
;             const size_t xhA = last ? nhA : hA, xhB = last ? nhB : hB;
;             PG8_LDB(B0, 0, 0); PG8_SCHED; PG8_LDA(At, 0, 0); PG8_STAGE(PG8_SA(1, 1), a1 + hA, vA0, vA1);
;             PG8_WAIT_L(8); PG8_BAR; PG8_WAIT_L(0); PG8_MMA(0, 0, At, B0); PG8_BAR; PG8_SCHED;
;             PG8_LDB(B1, 0, 1); PG8_STAGE(PG8_SB(0, 0), b2, xB0, xB1);
;             PG8_BAR; PG8_WAIT_L(0); PG8_MMA(0, 1, At, B1); PG8_BAR;
;             PG8_LDA(At, 0, 1); PG8_STAGE(PG8_SA(0, 0), a2, xA0, xA1);
;             PG8_BAR; PG8_WAIT_L(0); PG8_MMA(1, 0, At, B0); PG8_BAR; PG8_SCHED;
.LBB0_745:
	s_add_u32 s23, s34, 0xfff80080
	s_addc_u32 s71, s35, -1
	s_and_b64 s[42:43], exec, s[42:43]
	s_cselect_b32 s43, s25, s71
	s_cselect_b32 s42, s24, s23
	s_add_i32 s23, 0, 0x10000
	v_add_u32_e32 v138, s23, v147
	ds_read_b128 v[150:153], v138
	ds_read_b128 v[154:157], v138 offset:1024
	ds_read_b128 v[158:161], v138 offset:2048
	ds_read_b128 v[182:185], v138 offset:3072
	v_lshl_add_u64 v[138:139], s[34:35], 0, v[136:137]
	s_add_i32 m0, s50, 0xc000
	ds_read_b128 v[186:189], v148
	ds_read_b128 v[190:193], v148 offset:1024
	ds_read_b128 v[194:197], v148 offset:2048
	ds_read_b128 v[198:201], v148 offset:3072
	ds_read_b128 v[202:205], v148 offset:4096
	ds_read_b128 v[206:209], v148 offset:5120
	ds_read_b128 v[210:213], v148 offset:6144
	ds_read_b128 v[214:217], v148 offset:7168
	global_load_lds_dwordx4 v[138:139], off
	v_lshl_add_u64 v[138:139], s[34:35], 0, v[132:133]
	s_add_i32 m0, s50, 0xe000
	s_nop 0
	global_load_lds_dwordx4 v[138:139], off
	s_waitcnt lgkmcnt(8)
	s_barrier
	s_waitcnt lgkmcnt(0)
	s_setprio 1
	s_waitcnt lgkmcnt(0)
	v_mfma_f32_16x16x32_bf16 v[124:127], v[150:153], v[186:189], v[124:127]
	v_mfma_f32_16x16x32_bf16 v[120:123], v[158:161], v[186:189], v[120:123]
	v_mfma_f32_16x16x32_bf16 v[108:111], v[150:153], v[194:197], v[108:111]
	v_mfma_f32_16x16x32_bf16 v[104:107], v[158:161], v[194:197], v[104:107]
	v_mfma_f32_16x16x32_bf16 v[92:95], v[150:153], v[202:205], v[92:95]
	v_mfma_f32_16x16x32_bf16 v[88:91], v[158:161], v[202:205], v[88:91]
	v_mfma_f32_16x16x32_bf16 v[76:79], v[150:153], v[210:213], v[76:79]
	v_mfma_f32_16x16x32_bf16 v[72:75], v[158:161], v[210:213], v[72:75]
	v_mfma_f32_16x16x32_bf16 v[124:127], v[154:157], v[190:193], v[124:127]
	v_mfma_f32_16x16x32_bf16 v[120:123], v[182:185], v[190:193], v[120:123]
	v_mfma_f32_16x16x32_bf16 v[108:111], v[154:157], v[198:201], v[108:111]
	v_mfma_f32_16x16x32_bf16 v[104:107], v[182:185], v[198:201], v[104:107]
	v_mfma_f32_16x16x32_bf16 v[92:95], v[154:157], v[206:209], v[92:95]
	v_mfma_f32_16x16x32_bf16 v[88:91], v[182:185], v[206:209], v[88:91]
	v_mfma_f32_16x16x32_bf16 v[76:79], v[154:157], v[214:217], v[76:79]
	v_mfma_f32_16x16x32_bf16 v[72:75], v[182:185], v[214:217], v[72:75]
	s_setprio 0
	s_barrier
	s_add_i32 s71, 0, 0x14000
	v_add_u32_e32 v138, s71, v147
	s_add_i32 s23, s23, s49
	ds_read_b128 v[218:221], v138
	ds_read_b128 v[222:225], v138 offset:1024
	ds_read_b128 v[226:229], v138 offset:2048
	ds_read_b128 v[230:233], v138 offset:3072
	v_lshl_add_u64 v[138:139], s[40:41], 0, v[142:143]
	s_mov_b32 m0, s23
	v_lshl_add_u64 v[140:141], s[40:41], 0, v[134:135]
	global_load_lds_dwordx4 v[138:139], off
	s_add_i32 m0, s23, 0x2000
	s_nop 0
	global_load_lds_dwordx4 v[140:141], off
	s_barrier
	s_waitcnt lgkmcnt(0)
	s_setprio 1
	s_waitcnt lgkmcnt(0)
	v_mfma_f32_16x16x32_bf16 v[116:119], v[218:221], v[186:189], v[116:119]
	v_mfma_f32_16x16x32_bf16 v[112:115], v[226:229], v[186:189], v[112:115]
	v_mfma_f32_16x16x32_bf16 v[100:103], v[218:221], v[194:197], v[100:103]
	v_mfma_f32_16x16x32_bf16 v[96:99], v[226:229], v[194:197], v[96:99]
	v_mfma_f32_16x16x32_bf16 v[84:87], v[218:221], v[202:205], v[84:87]
	v_mfma_f32_16x16x32_bf16 v[80:83], v[226:229], v[202:205], v[80:83]
	v_mfma_f32_16x16x32_bf16 v[68:71], v[218:221], v[210:213], v[68:71]
	v_mfma_f32_16x16x32_bf16 v[64:67], v[226:229], v[210:213], v[64:67]
	v_mfma_f32_16x16x32_bf16 v[116:119], v[222:225], v[190:193], v[116:119]
	v_mfma_f32_16x16x32_bf16 v[112:115], v[230:233], v[190:193], v[112:115]
	v_mfma_f32_16x16x32_bf16 v[100:103], v[222:225], v[198:201], v[100:103]
	v_mfma_f32_16x16x32_bf16 v[96:99], v[230:233], v[198:201], v[96:99]
	v_mfma_f32_16x16x32_bf16 v[84:87], v[222:225], v[206:209], v[84:87]
	v_mfma_f32_16x16x32_bf16 v[80:83], v[230:233], v[206:209], v[80:83]
	v_mfma_f32_16x16x32_bf16 v[68:71], v[222:225], v[214:217], v[68:71]
	v_mfma_f32_16x16x32_bf16 v[64:67], v[230:233], v[214:217], v[64:67]
	s_setprio 0
	s_mov_b32 m0, s50
	v_lshl_add_u64 v[234:235], s[42:43], 0, v[142:143]
	s_barrier
	ds_read_b128 v[186:189], v148 offset:16384
	ds_read_b128 v[190:193], v148 offset:17408
	ds_read_b128 v[194:197], v148 offset:18432
	ds_read_b128 v[198:201], v148 offset:19456
	ds_read_b128 v[202:205], v148 offset:20480
	ds_read_b128 v[206:209], v148 offset:21504
	ds_read_b128 v[210:213], v148 offset:22528
	ds_read_b128 v[214:217], v148 offset:23552
	global_load_lds_dwordx4 v[234:235], off
	v_lshl_add_u64 v[236:237], s[42:43], 0, v[134:135]
	s_mov_b32 m0, s51
	s_nop 0
	global_load_lds_dwordx4 v[236:237], off
	s_barrier
	s_waitcnt lgkmcnt(0)
	s_setprio 1
	s_waitcnt lgkmcnt(0)
	v_mfma_f32_16x16x32_bf16 v[60:63], v[150:153], v[186:189], v[60:63]
	v_mfma_f32_16x16x32_bf16 v[56:59], v[158:161], v[186:189], v[56:59]
	v_mfma_f32_16x16x32_bf16 v[44:47], v[150:153], v[194:197], v[44:47]
	v_mfma_f32_16x16x32_bf16 v[40:43], v[158:161], v[194:197], v[40:43]
	v_mfma_f32_16x16x32_bf16 v[28:31], v[150:153], v[202:205], v[28:31]
	v_mfma_f32_16x16x32_bf16 v[24:27], v[158:161], v[202:205], v[24:27]
	v_mfma_f32_16x16x32_bf16 v[12:15], v[150:153], v[210:213], v[12:15]
	v_mfma_f32_16x16x32_bf16 v[8:11], v[158:161], v[210:213], v[8:11]
	v_mfma_f32_16x16x32_bf16 v[60:63], v[154:157], v[190:193], v[60:63]
	v_mfma_f32_16x16x32_bf16 v[56:59], v[182:185], v[190:193], v[56:59]
	v_mfma_f32_16x16x32_bf16 v[44:47], v[154:157], v[198:201], v[44:47]
	v_mfma_f32_16x16x32_bf16 v[40:43], v[182:185], v[198:201], v[40:43]
	v_mfma_f32_16x16x32_bf16 v[28:31], v[154:157], v[206:209], v[28:31]
	v_mfma_f32_16x16x32_bf16 v[24:27], v[182:185], v[206:209], v[24:27]
	v_mfma_f32_16x16x32_bf16 v[12:15], v[154:157], v[214:217], v[12:15]
	v_mfma_f32_16x16x32_bf16 v[8:11], v[182:185], v[214:217], v[8:11]
	s_setprio 0
	s_barrier
; #define PG8_STAGE(bufoff, gbase, v0, v1) do { \
;         __builtin_amdgcn_global_load_lds((const unsigned*)((const char*)(gbase) + (v0)), (LAS unsigned*)(lds + (bufoff) + ldsw), 16, 0, 0); \
;         __builtin_amdgcn_global_load_lds((const unsigned*)((const char*)(gbase) + (v1)), (LAS unsigned*)(lds + (bufoff) + ldsw + 8192), 16, 0, 0); } while (0)
; #define PG8_LDA(dst, b, h) do { _Pragma("unroll") for (int m = 0; m < 4; ++m) _Pragma("unroll") for (int k = 0; k < 2; ++k) dst[m][k] = *(const LAS bf16x8*)(lds + PG8_SA(b, h) + aoff + m * 2048 + k * 1024); } while (0)
; #define PG8_LDB(dst, b, h) do { _Pragma("unroll") for (int n = 0; n < 2; ++n) _Pragma("unroll") for (int k = 0; k < 2; ++k) dst[n][k] = *(const LAS bf16x8*)(lds + PG8_SB(b, h) + boff + n * 2048 + k * 1024); } while (0)
; #define PG8_MMA(ai, bj, At, Bt) do { __builtin_amdgcn_s_setprio(1); _Pragma("unroll") for (int m = 0; m < 4; ++m) _Pragma("unroll") for (int n = 0; n < 2; ++n) _Pragma("unroll") for (int k = 0; k < 2; ++k) \
;         acc[ai][bj][m][n] = __builtin_amdgcn_mfma_f32_16x16x32_bf16(Bt[n][k], At[m][k], acc[ai][bj][m][n], 0, 0, 0); __builtin_amdgcn_s_setprio(0); } while (0)
; #define PG8_WAIT_V(n) asm volatile("s_waitcnt vmcnt(" #n ")" ::: "memory")
; #define PG8_WAIT_L(n) asm volatile("s_waitcnt lgkmcnt(" #n ")" ::: "memory")
; #define PG8_BAR __builtin_amdgcn_s_barrier()
; #define PG8_SCHED __builtin_amdgcn_sched_barrier(0)
; template <class Epi, class Sched>
; __device__ __forceinline__ void gemm_phase(LAS unsigned char* lds, const Sched& S, const Epi& E) {
;     ...
;             PG8_STAGE(PG8_SB(0, 1), b2 + xhB, xB0, xB1);
;             PG8_WAIT_V(6); PG8_BAR; PG8_MMA(1, 1, At, B1); PG8_BAR;
;             PG8_LDB(B0, 1, 0); PG8_SCHED; PG8_LDA(At, 1, 0); PG8_STAGE(PG8_SA(0, 1), a2 + xhA, xA0, xA1);
;             PG8_WAIT_L(8); PG8_BAR; PG8_WAIT_L(0); PG8_MMA(0, 0, At, B0); PG8_BAR; PG8_SCHED;
;             PG8_LDB(B1, 1, 1); PG8_STAGE(PG8_SB(1, 0), b3, xB0, xB1);
	s_add_u32 s82, s40, 0x80000
	s_addc_u32 s83, s41, 0
	s_add_i32 s23, s71, s49
	v_lshl_add_u64 v[150:151], s[82:83], 0, v[142:143]
	s_mov_b32 m0, s23
	s_nop 0
	global_load_lds_dwordx4 v[150:151], off
	v_lshl_add_u64 v[150:151], s[82:83], 0, v[134:135]
	s_add_i32 m0, s23, 0x2000
	s_nop 0
	global_load_lds_dwordx4 v[150:151], off
	s_waitcnt vmcnt(6)
	s_barrier
	s_setprio 1
	v_mfma_f32_16x16x32_bf16 v[52:55], v[218:221], v[186:189], v[52:55]
	v_mfma_f32_16x16x32_bf16 v[48:51], v[226:229], v[186:189], v[48:51]
	v_mfma_f32_16x16x32_bf16 v[36:39], v[218:221], v[194:197], v[36:39]
	v_mfma_f32_16x16x32_bf16 v[32:35], v[226:229], v[194:197], v[32:35]
	v_mfma_f32_16x16x32_bf16 v[20:23], v[218:221], v[202:205], v[20:23]
	v_mfma_f32_16x16x32_bf16 v[16:19], v[226:229], v[202:205], v[16:19]
	v_mfma_f32_16x16x32_bf16 v[4:7], v[218:221], v[210:213], v[4:7]
	v_mfma_f32_16x16x32_bf16 v[0:3], v[226:229], v[210:213], v[0:3]
	v_mfma_f32_16x16x32_bf16 v[52:55], v[222:225], v[190:193], v[52:55]
	v_mfma_f32_16x16x32_bf16 v[48:51], v[230:233], v[190:193], v[48:51]
	v_mfma_f32_16x16x32_bf16 v[36:39], v[222:225], v[198:201], v[36:39]
	v_mfma_f32_16x16x32_bf16 v[32:35], v[230:233], v[198:201], v[32:35]
	v_mfma_f32_16x16x32_bf16 v[20:23], v[222:225], v[206:209], v[20:23]
	v_mfma_f32_16x16x32_bf16 v[16:19], v[230:233], v[206:209], v[16:19]
	v_mfma_f32_16x16x32_bf16 v[4:7], v[222:225], v[214:217], v[4:7]
	v_mfma_f32_16x16x32_bf16 v[0:3], v[230:233], v[214:217], v[0:3]
	s_setprio 0
	s_add_i32 s23, 0, 0x18000
	v_add_u32_e32 v149, s23, v147
	s_barrier
	ds_read_b128 v[150:153], v149
	ds_read_b128 v[154:157], v149 offset:1024
	ds_read_b128 v[158:161], v149 offset:2048
	ds_read_b128 v[182:185], v149 offset:3072
	s_add_u32 s42, s42, 0x80000
	s_addc_u32 s43, s43, 0
	s_mov_b32 m0, s54
	v_lshl_add_u64 v[218:219], s[42:43], 0, v[142:143]
	ds_read_b128 v[186:189], v148 offset:32768
	ds_read_b128 v[190:193], v148 offset:33792
	ds_read_b128 v[194:197], v148 offset:34816
	ds_read_b128 v[198:201], v148 offset:35840
	ds_read_b128 v[202:205], v148 offset:36864
	ds_read_b128 v[206:209], v148 offset:37888
	ds_read_b128 v[210:213], v148 offset:38912
	ds_read_b128 v[214:217], v148 offset:39936
	global_load_lds_dwordx4 v[218:219], off
	v_lshl_add_u64 v[218:219], s[42:43], 0, v[134:135]
	s_mov_b32 m0, s55
	s_nop 0
	global_load_lds_dwordx4 v[218:219], off
	s_waitcnt lgkmcnt(8)
	s_barrier
	s_waitcnt lgkmcnt(0)
	s_setprio 1
	s_waitcnt lgkmcnt(0)
	v_mfma_f32_16x16x32_bf16 v[124:127], v[150:153], v[186:189], v[124:127]
	v_mfma_f32_16x16x32_bf16 v[120:123], v[158:161], v[186:189], v[120:123]
	v_mfma_f32_16x16x32_bf16 v[108:111], v[150:153], v[194:197], v[108:111]
	v_mfma_f32_16x16x32_bf16 v[104:107], v[158:161], v[194:197], v[104:107]
	v_mfma_f32_16x16x32_bf16 v[92:95], v[150:153], v[202:205], v[92:95]
	v_mfma_f32_16x16x32_bf16 v[88:91], v[158:161], v[202:205], v[88:91]
	v_mfma_f32_16x16x32_bf16 v[76:79], v[150:153], v[210:213], v[76:79]
	v_mfma_f32_16x16x32_bf16 v[72:75], v[158:161], v[210:213], v[72:75]
	v_mfma_f32_16x16x32_bf16 v[124:127], v[154:157], v[190:193], v[124:127]
	v_mfma_f32_16x16x32_bf16 v[120:123], v[182:185], v[190:193], v[120:123]
	v_mfma_f32_16x16x32_bf16 v[108:111], v[154:157], v[198:201], v[108:111]
	v_mfma_f32_16x16x32_bf16 v[104:107], v[182:185], v[198:201], v[104:107]
	v_mfma_f32_16x16x32_bf16 v[92:95], v[154:157], v[206:209], v[92:95]
	v_mfma_f32_16x16x32_bf16 v[88:91], v[182:185], v[206:209], v[88:91]
	v_mfma_f32_16x16x32_bf16 v[76:79], v[154:157], v[214:217], v[76:79]
	v_mfma_f32_16x16x32_bf16 v[72:75], v[182:185], v[214:217], v[72:75]
	s_setprio 0
	s_barrier
	s_add_i32 s42, 0, 0x1c000
	s_add_i32 s23, s23, s49
	v_add_u32_e32 v149, s42, v147
	v_lshl_add_u64 v[138:139], v[138:139], 0, s[44:45]
	s_mov_b32 m0, s23
	ds_read_b128 v[218:221], v149
	ds_read_b128 v[222:225], v149 offset:1024
	ds_read_b128 v[226:229], v149 offset:2048
	ds_read_b128 v[230:233], v149 offset:3072
	global_load_lds_dwordx4 v[138:139], off
	v_lshl_add_u64 v[138:139], v[140:141], 0, s[44:45]
	s_add_i32 m0, s23, 0x2000
	s_nop 0
	global_load_lds_dwordx4 v[138:139], off
	s_barrier
; #define PG8_STAGE(bufoff, gbase, v0, v1) do { \
;         __builtin_amdgcn_global_load_lds((const unsigned*)((const char*)(gbase) + (v0)), (LAS unsigned*)(lds + (bufoff) + ldsw), 16, 0, 0); \
;         __builtin_amdgcn_global_load_lds((const unsigned*)((const char*)(gbase) + (v1)), (LAS unsigned*)(lds + (bufoff) + ldsw + 8192), 16, 0, 0); } while (0)
; #define PG8_LDA(dst, b, h) do { _Pragma("unroll") for (int m = 0; m < 4; ++m) _Pragma("unroll") for (int k = 0; k < 2; ++k) dst[m][k] = *(const LAS bf16x8*)(lds + PG8_SA(b, h) + aoff + m * 2048 + k * 1024); } while (0)
; #define PG8_MMA(ai, bj, At, Bt) do { __builtin_amdgcn_s_setprio(1); _Pragma("unroll") for (int m = 0; m < 4; ++m) _Pragma("unroll") for (int n = 0; n < 2; ++n) _Pragma("unroll") for (int k = 0; k < 2; ++k) \
;         acc[ai][bj][m][n] = __builtin_amdgcn_mfma_f32_16x16x32_bf16(Bt[n][k], At[m][k], acc[ai][bj][m][n], 0, 0, 0); __builtin_amdgcn_s_setprio(0); } while (0)
; #define PG8_WAIT_V(n) asm volatile("s_waitcnt vmcnt(" #n ")" ::: "memory")
; #define PG8_WAIT_L(n) asm volatile("s_waitcnt lgkmcnt(" #n ")" ::: "memory")
; #define PG8_BAR __builtin_amdgcn_s_barrier()
; #define PG8_SCHED __builtin_amdgcn_sched_barrier(0)
; template <class Epi, class Sched>
; __device__ __forceinline__ void gemm_phase(LAS unsigned char* lds, const Sched& S, const Epi& E) {
;     ...
;             const bool last = (t == nt - 2);
;             const char* a1 = cA + (size_t)(t + 1) * kstep;
;             const char* a2 = last ? nA : cA + (size_t)(t + 2) * kstep; const char* b2 = last ? nB : cB + (size_t)(t + 2) * kstep;
;             const char* a3 = a2 + kstep; const char* b3 = b2 + kstep;
;             const unsigned xA0 = last ? nvA0 : vA0, xA1 = last ? nvA1 : vA1, xB0 = last ? nvB0 : vB0, xB1 = last ? nvB1 : vB1;
;             const size_t xhA = last ? nhA : hA, xhB = last ? nhB : hB;
;     ...
;             PG8_BAR; PG8_WAIT_L(0); PG8_MMA(0, 1, At, B1); PG8_BAR;
;             PG8_LDA(At, 1, 1); PG8_STAGE(PG8_SA(1, 0), a3, xA0, xA1);
;             PG8_BAR; PG8_WAIT_L(0); PG8_MMA(1, 0, At, B0); PG8_BAR; PG8_SCHED;
;             PG8_STAGE(PG8_SB(1, 1), b3 + xhB, xB0, xB1);
;             PG8_WAIT_V(6); PG8_BAR; PG8_MMA(1, 1, At, B1); PG8_BAR;
	s_waitcnt lgkmcnt(0)
	s_setprio 1
	s_waitcnt lgkmcnt(0)
	v_mfma_f32_16x16x32_bf16 v[116:119], v[218:221], v[186:189], v[116:119]
	v_mfma_f32_16x16x32_bf16 v[112:115], v[226:229], v[186:189], v[112:115]
	v_mfma_f32_16x16x32_bf16 v[100:103], v[218:221], v[194:197], v[100:103]
	v_mfma_f32_16x16x32_bf16 v[96:99], v[226:229], v[194:197], v[96:99]
	v_mfma_f32_16x16x32_bf16 v[84:87], v[218:221], v[202:205], v[84:87]
	v_mfma_f32_16x16x32_bf16 v[80:83], v[226:229], v[202:205], v[80:83]
	v_mfma_f32_16x16x32_bf16 v[68:71], v[218:221], v[210:213], v[68:71]
	v_mfma_f32_16x16x32_bf16 v[64:67], v[226:229], v[210:213], v[64:67]
	v_mfma_f32_16x16x32_bf16 v[116:119], v[222:225], v[190:193], v[116:119]
	v_mfma_f32_16x16x32_bf16 v[112:115], v[230:233], v[190:193], v[112:115]
	v_mfma_f32_16x16x32_bf16 v[100:103], v[222:225], v[198:201], v[100:103]
	v_mfma_f32_16x16x32_bf16 v[96:99], v[230:233], v[198:201], v[96:99]
	v_mfma_f32_16x16x32_bf16 v[84:87], v[222:225], v[206:209], v[84:87]
	v_mfma_f32_16x16x32_bf16 v[80:83], v[230:233], v[206:209], v[80:83]
	v_mfma_f32_16x16x32_bf16 v[68:71], v[222:225], v[214:217], v[68:71]
	v_mfma_f32_16x16x32_bf16 v[64:67], v[230:233], v[214:217], v[64:67]
	s_setprio 0
	s_mov_b32 m0, s66
	v_lshl_add_u64 v[138:139], v[234:235], 0, s[44:45]
	s_barrier
	ds_read_b128 v[186:189], v148 offset:49152
	ds_read_b128 v[190:193], v148 offset:50176
	ds_read_b128 v[194:197], v148 offset:51200
	ds_read_b128 v[198:201], v148 offset:52224
	ds_read_b128 v[202:205], v148 offset:53248
	ds_read_b128 v[206:209], v148 offset:54272
	ds_read_b128 v[210:213], v148 offset:55296
	ds_read_b128 v[214:217], v148 offset:56320
	global_load_lds_dwordx4 v[138:139], off
	v_lshl_add_u64 v[138:139], v[236:237], 0, s[44:45]
	s_mov_b32 m0, s67
	s_nop 0
	global_load_lds_dwordx4 v[138:139], off
	s_barrier
	s_waitcnt lgkmcnt(0)
	s_setprio 1
	s_waitcnt lgkmcnt(0)
	v_mfma_f32_16x16x32_bf16 v[60:63], v[150:153], v[186:189], v[60:63]
	v_mfma_f32_16x16x32_bf16 v[56:59], v[158:161], v[186:189], v[56:59]
	v_mfma_f32_16x16x32_bf16 v[44:47], v[150:153], v[194:197], v[44:47]
	v_mfma_f32_16x16x32_bf16 v[40:43], v[158:161], v[194:197], v[40:43]
	v_mfma_f32_16x16x32_bf16 v[28:31], v[150:153], v[202:205], v[28:31]
	v_mfma_f32_16x16x32_bf16 v[24:27], v[158:161], v[202:205], v[24:27]
	v_mfma_f32_16x16x32_bf16 v[12:15], v[150:153], v[210:213], v[12:15]
	v_mfma_f32_16x16x32_bf16 v[8:11], v[158:161], v[210:213], v[8:11]
	v_mfma_f32_16x16x32_bf16 v[60:63], v[154:157], v[190:193], v[60:63]
	v_mfma_f32_16x16x32_bf16 v[56:59], v[182:185], v[190:193], v[56:59]
	v_mfma_f32_16x16x32_bf16 v[44:47], v[154:157], v[198:201], v[44:47]
	v_mfma_f32_16x16x32_bf16 v[40:43], v[182:185], v[198:201], v[40:43]
	v_mfma_f32_16x16x32_bf16 v[28:31], v[154:157], v[206:209], v[28:31]
	v_mfma_f32_16x16x32_bf16 v[24:27], v[182:185], v[206:209], v[24:27]
	v_mfma_f32_16x16x32_bf16 v[12:15], v[154:157], v[214:217], v[12:15]
	v_mfma_f32_16x16x32_bf16 v[8:11], v[182:185], v[214:217], v[8:11]
	s_setprio 0
	s_barrier
	s_add_u32 s40, s40, 0x80080
	s_addc_u32 s41, s41, 0
	s_add_i32 s23, s42, s49
	v_lshl_add_u64 v[138:139], s[40:41], 0, v[142:143]
	s_mov_b32 m0, s23
	v_lshl_add_u64 v[134:135], s[40:41], 0, v[134:135]
	global_load_lds_dwordx4 v[138:139], off
	s_add_i32 m0, s23, 0x2000
	s_nop 0
	global_load_lds_dwordx4 v[134:135], off
	s_waitcnt vmcnt(6)
	s_barrier
	s_setprio 1
	v_mfma_f32_16x16x32_bf16 v[52:55], v[218:221], v[186:189], v[52:55]
	v_mfma_f32_16x16x32_bf16 v[48:51], v[226:229], v[186:189], v[48:51]
	v_mfma_f32_16x16x32_bf16 v[36:39], v[218:221], v[194:197], v[36:39]
	v_mfma_f32_16x16x32_bf16 v[32:35], v[226:229], v[194:197], v[32:35]
	v_mfma_f32_16x16x32_bf16 v[20:23], v[218:221], v[202:205], v[20:23]
	v_mfma_f32_16x16x32_bf16 v[16:19], v[226:229], v[202:205], v[16:19]
	v_mfma_f32_16x16x32_bf16 v[4:7], v[218:221], v[210:213], v[4:7]
	v_mfma_f32_16x16x32_bf16 v[0:3], v[226:229], v[210:213], v[0:3]
	v_mfma_f32_16x16x32_bf16 v[52:55], v[222:225], v[190:193], v[52:55]
	v_mfma_f32_16x16x32_bf16 v[48:51], v[230:233], v[190:193], v[48:51]
	v_mfma_f32_16x16x32_bf16 v[36:39], v[222:225], v[198:201], v[36:39]
	v_mfma_f32_16x16x32_bf16 v[32:35], v[230:233], v[198:201], v[32:35]
	v_mfma_f32_16x16x32_bf16 v[20:23], v[222:225], v[206:209], v[20:23]
	v_mfma_f32_16x16x32_bf16 v[16:19], v[230:233], v[206:209], v[16:19]
	v_mfma_f32_16x16x32_bf16 v[4:7], v[222:225], v[214:217], v[4:7]
	v_mfma_f32_16x16x32_bf16 v[0:3], v[230:233], v[214:217], v[0:3]
	s_setprio 0
	s_add_i32 s21, s21, 2
	s_add_u32 s34, s34, 0x100
	s_addc_u32 s35, s35, 0
	s_add_u32 s38, s38, 0x100
	s_addc_u32 s39, s39, 0
	s_cmp_gt_u32 s21, 29
	s_cbranch_scc1 .Lrot_exit_2
	s_cmp_eq_u32 s21, 28
	s_cselect_b64 s[42:43], -1, 0
	s_and_b64 vcc, exec, s[42:43]
	v_mov_b64_e32 v[134:135], v[130:131]
	v_mov_b64_e32 v[142:143], v[128:129]
	s_mov_b64 s[40:41], s[26:27]
	s_cbranch_vccnz .Lrot_join_2
	v_mov_b64_e32 v[134:135], v[132:133]
	v_mov_b64_e32 v[142:143], v[136:137]
	s_mov_b64 s[40:41], s[38:39]

; #define PG8_STAGE(bufoff, gbase, v0, v1) do { \
;         __builtin_amdgcn_global_load_lds((const unsigned*)((const char*)(gbase) + (v0)), (LAS unsigned*)(lds + (bufoff) + ldsw), 16, 0, 0); \
;         __builtin_amdgcn_global_load_lds((const unsigned*)((const char*)(gbase) + (v1)), (LAS unsigned*)(lds + (bufoff) + ldsw + 8192), 16, 0, 0); } while (0)
; #define PG8_LDA(dst, b, h) do { _Pragma("unroll") for (int m = 0; m < 4; ++m) _Pragma("unroll") for (int k = 0; k < 2; ++k) dst[m][k] = *(const LAS bf16x8*)(lds + PG8_SA(b, h) + aoff + m * 2048 + k * 1024); } while (0)
; #define PG8_LDB(dst, b, h) do { _Pragma("unroll") for (int n = 0; n < 2; ++n) _Pragma("unroll") for (int k = 0; k < 2; ++k) dst[n][k] = *(const LAS bf16x8*)(lds + PG8_SB(b, h) + boff + n * 2048 + k * 1024); } while (0)
; #define PG8_MMA(ai, bj, At, Bt) do { __builtin_amdgcn_s_setprio(1); _Pragma("unroll") for (int m = 0; m < 4; ++m) _Pragma("unroll") for (int n = 0; n < 2; ++n) _Pragma("unroll") for (int k = 0; k < 2; ++k) \
;         acc[ai][bj][m][n] = __builtin_amdgcn_mfma_f32_16x16x32_bf16(Bt[n][k], At[m][k], acc[ai][bj][m][n], 0, 0, 0); __builtin_amdgcn_s_setprio(0); } while (0)
; #define PG8_WAIT_L(n) asm volatile("s_waitcnt lgkmcnt(" #n ")" ::: "memory")
; template <class Epi, class Sched>
; __device__ __forceinline__ void gemm_phase(LAS unsigned char* lds, const Sched& S, const Epi& E) {
;     ...
;             const bool last = (t == nt - 2);
;             const char* a1 = cA + (size_t)(t + 1) * kstep;
;             const char* a2 = last ? nA : cA + (size_t)(t + 2) * kstep; const char* b2 = last ? nB : cB + (size_t)(t + 2) * kstep;
;             const char* a3 = a2 + kstep; const char* b3 = b2 + kstep;
;             const unsigned xA0 = last ? nvA0 : vA0, xA1 = last ? nvA1 : vA1, xB0 = last ? nvB0 : vB0, xB1 = last ? nvB1 : vB1;
;             const size_t xhA = last ? nhA : hA, xhB = last ? nhB : hB;
;             PG8_LDB(B0, 0, 0); PG8_SCHED; PG8_LDA(At, 0, 0); PG8_STAGE(PG8_SA(1, 1), a1 + hA, vA0, vA1);
;             PG8_WAIT_L(8); PG8_BAR; PG8_WAIT_L(0); PG8_MMA(0, 0, At, B0); PG8_BAR; PG8_SCHED;
;             PG8_LDB(B1, 0, 1); PG8_STAGE(PG8_SB(0, 0), b2, xB0, xB1);
;             PG8_BAR; PG8_WAIT_L(0); PG8_MMA(0, 1, At, B1); PG8_BAR;
;             PG8_LDA(At, 0, 1); PG8_STAGE(PG8_SA(0, 0), a2, xA0, xA1);
;             PG8_BAR; PG8_WAIT_L(0); PG8_MMA(1, 0, At, B0); PG8_BAR; PG8_SCHED;
.LBB0_808:
	s_add_u32 s21, s26, 0xfff80080
	s_addc_u32 s69, s27, -1
	s_and_b64 s[40:41], exec, s[40:41]
	s_cselect_b32 s41, s23, s69
	s_cselect_b32 s40, s22, s21
	s_add_i32 s21, 0, 0x10000
	v_add_u32_e32 v138, s21, v155
	ds_read_b128 v[158:161], v138
	ds_read_b128 v[182:185], v138 offset:1024
	ds_read_b128 v[186:189], v138 offset:2048
	ds_read_b128 v[190:193], v138 offset:3072
	v_lshl_add_u64 v[138:139], s[26:27], 0, v[132:133]
	s_add_i32 m0, s48, 0xc000
	ds_read_b128 v[194:197], v143
	ds_read_b128 v[198:201], v143 offset:1024
	ds_read_b128 v[202:205], v143 offset:2048
	ds_read_b128 v[206:209], v143 offset:3072
	ds_read_b128 v[210:213], v143 offset:4096
	ds_read_b128 v[214:217], v143 offset:5120
	ds_read_b128 v[218:221], v143 offset:6144
	ds_read_b128 v[222:225], v143 offset:7168
	global_load_lds_dwordx4 v[138:139], off
	v_lshl_add_u64 v[138:139], s[26:27], 0, v[134:135]
	s_add_i32 m0, s48, 0xe000
	s_nop 0
	global_load_lds_dwordx4 v[138:139], off
	s_waitcnt lgkmcnt(8)
	s_barrier
	s_waitcnt lgkmcnt(0)
	s_setprio 1
	s_waitcnt lgkmcnt(0)
	v_mfma_f32_16x16x32_bf16 v[124:127], v[158:161], v[194:197], v[124:127]
	v_mfma_f32_16x16x32_bf16 v[120:123], v[186:189], v[194:197], v[120:123]
	v_mfma_f32_16x16x32_bf16 v[112:115], v[158:161], v[202:205], v[112:115]
	v_mfma_f32_16x16x32_bf16 v[104:107], v[186:189], v[202:205], v[104:107]
	v_mfma_f32_16x16x32_bf16 v[96:99], v[158:161], v[210:213], v[96:99]
	v_mfma_f32_16x16x32_bf16 v[88:91], v[186:189], v[210:213], v[88:91]
	v_mfma_f32_16x16x32_bf16 v[80:83], v[158:161], v[218:221], v[80:83]
	v_mfma_f32_16x16x32_bf16 v[72:75], v[186:189], v[218:221], v[72:75]
	v_mfma_f32_16x16x32_bf16 v[124:127], v[182:185], v[198:201], v[124:127]
	v_mfma_f32_16x16x32_bf16 v[120:123], v[190:193], v[198:201], v[120:123]
	v_mfma_f32_16x16x32_bf16 v[112:115], v[182:185], v[206:209], v[112:115]
	v_mfma_f32_16x16x32_bf16 v[104:107], v[190:193], v[206:209], v[104:107]
	v_mfma_f32_16x16x32_bf16 v[96:99], v[182:185], v[214:217], v[96:99]
	v_mfma_f32_16x16x32_bf16 v[88:91], v[190:193], v[214:217], v[88:91]
	v_mfma_f32_16x16x32_bf16 v[80:83], v[182:185], v[222:225], v[80:83]
	v_mfma_f32_16x16x32_bf16 v[72:75], v[190:193], v[222:225], v[72:75]
	s_setprio 0
	s_barrier
	s_add_i32 s69, 0, 0x14000
	s_add_i32 s21, s21, s43
	v_add_u32_e32 v138, s69, v155
	s_mov_b32 m0, s21
	ds_read_b128 v[226:229], v138
	ds_read_b128 v[230:233], v138 offset:1024
	ds_read_b128 v[234:237], v138 offset:2048
	ds_read_b128 v[238:241], v138 offset:3072
	global_load_lds_dwordx4 v136, s[38:39]
	s_add_i32 m0, s21, 0x2000
	v_mov_b32_e32 v147, v137
	global_load_lds_dwordx4 v146, s[38:39]
	s_barrier
	s_waitcnt lgkmcnt(0)
	v_lshl_add_u64 v[138:139], s[38:39], 0, v[136:137]
	v_lshl_add_u64 v[140:141], s[38:39], 0, v[146:147]
	s_setprio 1
	s_waitcnt lgkmcnt(0)
	v_mfma_f32_16x16x32_bf16 v[116:119], v[226:229], v[194:197], v[116:119]
	v_mfma_f32_16x16x32_bf16 v[108:111], v[234:237], v[194:197], v[108:111]
	v_mfma_f32_16x16x32_bf16 v[100:103], v[226:229], v[202:205], v[100:103]
	v_mfma_f32_16x16x32_bf16 v[92:95], v[234:237], v[202:205], v[92:95]
	v_mfma_f32_16x16x32_bf16 v[84:87], v[226:229], v[210:213], v[84:87]
	v_mfma_f32_16x16x32_bf16 v[76:79], v[234:237], v[210:213], v[76:79]
	v_mfma_f32_16x16x32_bf16 v[68:71], v[226:229], v[218:221], v[68:71]
	v_mfma_f32_16x16x32_bf16 v[64:67], v[234:237], v[218:221], v[64:67]
	v_mfma_f32_16x16x32_bf16 v[116:119], v[230:233], v[198:201], v[116:119]
	v_mfma_f32_16x16x32_bf16 v[108:111], v[238:241], v[198:201], v[108:111]
	v_mfma_f32_16x16x32_bf16 v[100:103], v[230:233], v[206:209], v[100:103]
	v_mfma_f32_16x16x32_bf16 v[92:95], v[238:241], v[206:209], v[92:95]
	v_mfma_f32_16x16x32_bf16 v[84:87], v[230:233], v[214:217], v[84:87]
	v_mfma_f32_16x16x32_bf16 v[76:79], v[238:241], v[214:217], v[76:79]
	v_mfma_f32_16x16x32_bf16 v[68:71], v[230:233], v[222:225], v[68:71]
	v_mfma_f32_16x16x32_bf16 v[64:67], v[238:241], v[222:225], v[64:67]
	s_setprio 0
	s_mov_b32 m0, s48
	v_lshl_add_u64 v[242:243], s[40:41], 0, v[150:151]
	s_barrier
	ds_read_b128 v[194:197], v143 offset:16384
	ds_read_b128 v[198:201], v143 offset:17408
	ds_read_b128 v[202:205], v143 offset:18432
	ds_read_b128 v[206:209], v143 offset:19456
	ds_read_b128 v[210:213], v143 offset:20480
	ds_read_b128 v[214:217], v143 offset:21504
	ds_read_b128 v[218:221], v143 offset:22528
	ds_read_b128 v[222:225], v143 offset:23552
	global_load_lds_dwordx4 v[242:243], off
	v_lshl_add_u64 v[244:245], s[40:41], 0, v[148:149]
	s_mov_b32 m0, s49
	s_nop 0
	global_load_lds_dwordx4 v[244:245], off
	s_barrier
	s_waitcnt lgkmcnt(0)
	s_setprio 1
	s_waitcnt lgkmcnt(0)
	v_mfma_f32_16x16x32_bf16 v[60:63], v[158:161], v[194:197], v[60:63]
	v_mfma_f32_16x16x32_bf16 v[56:59], v[186:189], v[194:197], v[56:59]
	v_mfma_f32_16x16x32_bf16 v[44:47], v[158:161], v[202:205], v[44:47]
	v_mfma_f32_16x16x32_bf16 v[40:43], v[186:189], v[202:205], v[40:43]
	v_mfma_f32_16x16x32_bf16 v[28:31], v[158:161], v[210:213], v[28:31]
	v_mfma_f32_16x16x32_bf16 v[24:27], v[186:189], v[210:213], v[24:27]
	v_mfma_f32_16x16x32_bf16 v[12:15], v[158:161], v[218:221], v[12:15]
	v_mfma_f32_16x16x32_bf16 v[8:11], v[186:189], v[218:221], v[8:11]
	v_mfma_f32_16x16x32_bf16 v[60:63], v[182:185], v[198:201], v[60:63]
	v_mfma_f32_16x16x32_bf16 v[56:59], v[190:193], v[198:201], v[56:59]
	v_mfma_f32_16x16x32_bf16 v[44:47], v[182:185], v[206:209], v[44:47]
	v_mfma_f32_16x16x32_bf16 v[40:43], v[190:193], v[206:209], v[40:43]
	v_mfma_f32_16x16x32_bf16 v[28:31], v[182:185], v[214:217], v[28:31]
	v_mfma_f32_16x16x32_bf16 v[24:27], v[190:193], v[214:217], v[24:27]
	v_mfma_f32_16x16x32_bf16 v[12:15], v[182:185], v[222:225], v[12:15]
	v_mfma_f32_16x16x32_bf16 v[8:11], v[190:193], v[222:225], v[8:11]
	s_setprio 0
	s_barrier
; #define PG8_STAGE(bufoff, gbase, v0, v1) do { \
;         __builtin_amdgcn_global_load_lds((const unsigned*)((const char*)(gbase) + (v0)), (LAS unsigned*)(lds + (bufoff) + ldsw), 16, 0, 0); \
;         __builtin_amdgcn_global_load_lds((const unsigned*)((const char*)(gbase) + (v1)), (LAS unsigned*)(lds + (bufoff) + ldsw + 8192), 16, 0, 0); } while (0)
; #define PG8_LDA(dst, b, h) do { _Pragma("unroll") for (int m = 0; m < 4; ++m) _Pragma("unroll") for (int k = 0; k < 2; ++k) dst[m][k] = *(const LAS bf16x8*)(lds + PG8_SA(b, h) + aoff + m * 2048 + k * 1024); } while (0)
; #define PG8_LDB(dst, b, h) do { _Pragma("unroll") for (int n = 0; n < 2; ++n) _Pragma("unroll") for (int k = 0; k < 2; ++k) dst[n][k] = *(const LAS bf16x8*)(lds + PG8_SB(b, h) + boff + n * 2048 + k * 1024); } while (0)
; #define PG8_MMA(ai, bj, At, Bt) do { __builtin_amdgcn_s_setprio(1); _Pragma("unroll") for (int m = 0; m < 4; ++m) _Pragma("unroll") for (int n = 0; n < 2; ++n) _Pragma("unroll") for (int k = 0; k < 2; ++k) \
;         acc[ai][bj][m][n] = __builtin_amdgcn_mfma_f32_16x16x32_bf16(Bt[n][k], At[m][k], acc[ai][bj][m][n], 0, 0, 0); __builtin_amdgcn_s_setprio(0); } while (0)
; #define PG8_WAIT_V(n) asm volatile("s_waitcnt vmcnt(" #n ")" ::: "memory")
; #define PG8_WAIT_L(n) asm volatile("s_waitcnt lgkmcnt(" #n ")" ::: "memory")
; #define PG8_BAR __builtin_amdgcn_s_barrier()
; #define PG8_SCHED __builtin_amdgcn_sched_barrier(0)
; template <class Epi, class Sched>
; __device__ __forceinline__ void gemm_phase(LAS unsigned char* lds, const Sched& S, const Epi& E) {
;     ...
;             PG8_STAGE(PG8_SB(0, 1), b2 + xhB, xB0, xB1);
;             PG8_WAIT_V(6); PG8_BAR; PG8_MMA(1, 1, At, B1); PG8_BAR;
;             PG8_LDB(B0, 1, 0); PG8_SCHED; PG8_LDA(At, 1, 0); PG8_STAGE(PG8_SA(0, 1), a2 + xhA, xA0, xA1);
;             PG8_WAIT_L(8); PG8_BAR; PG8_WAIT_L(0); PG8_MMA(0, 0, At, B0); PG8_BAR; PG8_SCHED;
;             PG8_LDB(B1, 1, 1); PG8_STAGE(PG8_SB(1, 0), b3, xB0, xB1);
	s_add_u32 s70, s38, 0x80000
	s_addc_u32 s71, s39, 0
	s_add_i32 s21, s69, s43
	s_mov_b32 m0, s21
	s_nop 0
	global_load_lds_dwordx4 v136, s[70:71]
	s_add_i32 m0, s21, 0x2000
	s_nop 0
	global_load_lds_dwordx4 v146, s[70:71]
	s_waitcnt vmcnt(6)
	s_barrier
	s_setprio 1
	v_mfma_f32_16x16x32_bf16 v[52:55], v[226:229], v[194:197], v[52:55]
	v_mfma_f32_16x16x32_bf16 v[48:51], v[234:237], v[194:197], v[48:51]
	v_mfma_f32_16x16x32_bf16 v[36:39], v[226:229], v[202:205], v[36:39]
	v_mfma_f32_16x16x32_bf16 v[32:35], v[234:237], v[202:205], v[32:35]
	v_mfma_f32_16x16x32_bf16 v[20:23], v[226:229], v[210:213], v[20:23]
	v_mfma_f32_16x16x32_bf16 v[16:19], v[234:237], v[210:213], v[16:19]
	v_mfma_f32_16x16x32_bf16 v[4:7], v[226:229], v[218:221], v[4:7]
	v_mfma_f32_16x16x32_bf16 v[0:3], v[234:237], v[218:221], v[0:3]
	v_mfma_f32_16x16x32_bf16 v[52:55], v[230:233], v[198:201], v[52:55]
	v_mfma_f32_16x16x32_bf16 v[48:51], v[238:241], v[198:201], v[48:51]
	v_mfma_f32_16x16x32_bf16 v[36:39], v[230:233], v[206:209], v[36:39]
	v_mfma_f32_16x16x32_bf16 v[32:35], v[238:241], v[206:209], v[32:35]
	v_mfma_f32_16x16x32_bf16 v[20:23], v[230:233], v[214:217], v[20:23]
	v_mfma_f32_16x16x32_bf16 v[16:19], v[238:241], v[214:217], v[16:19]
	v_mfma_f32_16x16x32_bf16 v[4:7], v[230:233], v[222:225], v[4:7]
	v_mfma_f32_16x16x32_bf16 v[0:3], v[238:241], v[222:225], v[0:3]
	s_setprio 0
	s_add_i32 s21, 0, 0x18000
	v_add_u32_e32 v147, s21, v155
	s_barrier
	ds_read_b128 v[158:161], v147
	ds_read_b128 v[182:185], v147 offset:1024
	ds_read_b128 v[186:189], v147 offset:2048
	ds_read_b128 v[190:193], v147 offset:3072
	s_add_u32 s40, s40, 0x80000
	s_addc_u32 s41, s41, 0
	s_mov_b32 m0, s50
	v_lshl_add_u64 v[150:151], s[40:41], 0, v[150:151]
	ds_read_b128 v[194:197], v143 offset:32768
	ds_read_b128 v[198:201], v143 offset:33792
	ds_read_b128 v[202:205], v143 offset:34816
	ds_read_b128 v[206:209], v143 offset:35840
	ds_read_b128 v[210:213], v143 offset:36864
	ds_read_b128 v[214:217], v143 offset:37888
	ds_read_b128 v[218:221], v143 offset:38912
	ds_read_b128 v[222:225], v143 offset:39936
	global_load_lds_dwordx4 v[150:151], off
	v_lshl_add_u64 v[148:149], s[40:41], 0, v[148:149]
	s_mov_b32 m0, s51
	s_nop 0
	global_load_lds_dwordx4 v[148:149], off
	s_waitcnt lgkmcnt(8)
	s_barrier
	s_waitcnt lgkmcnt(0)
	s_setprio 1
	s_waitcnt lgkmcnt(0)
	v_mfma_f32_16x16x32_bf16 v[124:127], v[158:161], v[194:197], v[124:127]
	v_mfma_f32_16x16x32_bf16 v[120:123], v[186:189], v[194:197], v[120:123]
	v_mfma_f32_16x16x32_bf16 v[112:115], v[158:161], v[202:205], v[112:115]
	v_mfma_f32_16x16x32_bf16 v[104:107], v[186:189], v[202:205], v[104:107]
	v_mfma_f32_16x16x32_bf16 v[96:99], v[158:161], v[210:213], v[96:99]
	v_mfma_f32_16x16x32_bf16 v[88:91], v[186:189], v[210:213], v[88:91]
	v_mfma_f32_16x16x32_bf16 v[80:83], v[158:161], v[218:221], v[80:83]
	v_mfma_f32_16x16x32_bf16 v[72:75], v[186:189], v[218:221], v[72:75]
	v_mfma_f32_16x16x32_bf16 v[124:127], v[182:185], v[198:201], v[124:127]
	v_mfma_f32_16x16x32_bf16 v[120:123], v[190:193], v[198:201], v[120:123]
	v_mfma_f32_16x16x32_bf16 v[112:115], v[182:185], v[206:209], v[112:115]
	v_mfma_f32_16x16x32_bf16 v[104:107], v[190:193], v[206:209], v[104:107]
	v_mfma_f32_16x16x32_bf16 v[96:99], v[182:185], v[214:217], v[96:99]
	v_mfma_f32_16x16x32_bf16 v[88:91], v[190:193], v[214:217], v[88:91]
	v_mfma_f32_16x16x32_bf16 v[80:83], v[182:185], v[222:225], v[80:83]
	v_mfma_f32_16x16x32_bf16 v[72:75], v[190:193], v[222:225], v[72:75]
	s_setprio 0
	s_barrier
	s_add_i32 s40, 0, 0x1c000
	s_add_i32 s21, s21, s43
	v_add_u32_e32 v147, s40, v155
	v_lshl_add_u64 v[138:139], v[138:139], 0, s[44:45]
	s_mov_b32 m0, s21
	ds_read_b128 v[148:151], v147
	ds_read_b128 v[226:229], v147 offset:1024
	ds_read_b128 v[230:233], v147 offset:2048
	ds_read_b128 v[234:237], v147 offset:3072
	global_load_lds_dwordx4 v[138:139], off
	v_lshl_add_u64 v[138:139], v[140:141], 0, s[44:45]
	s_add_i32 m0, s21, 0x2000
	s_nop 0
	global_load_lds_dwordx4 v[138:139], off
	s_barrier
; #define PG8_STAGE(bufoff, gbase, v0, v1) do { \
;         __builtin_amdgcn_global_load_lds((const unsigned*)((const char*)(gbase) + (v0)), (LAS unsigned*)(lds + (bufoff) + ldsw), 16, 0, 0); \
;         __builtin_amdgcn_global_load_lds((const unsigned*)((const char*)(gbase) + (v1)), (LAS unsigned*)(lds + (bufoff) + ldsw + 8192), 16, 0, 0); } while (0)
; #define PG8_LDA(dst, b, h) do { _Pragma("unroll") for (int m = 0; m < 4; ++m) _Pragma("unroll") for (int k = 0; k < 2; ++k) dst[m][k] = *(const LAS bf16x8*)(lds + PG8_SA(b, h) + aoff + m * 2048 + k * 1024); } while (0)
; #define PG8_MMA(ai, bj, At, Bt) do { __builtin_amdgcn_s_setprio(1); _Pragma("unroll") for (int m = 0; m < 4; ++m) _Pragma("unroll") for (int n = 0; n < 2; ++n) _Pragma("unroll") for (int k = 0; k < 2; ++k) \
;         acc[ai][bj][m][n] = __builtin_amdgcn_mfma_f32_16x16x32_bf16(Bt[n][k], At[m][k], acc[ai][bj][m][n], 0, 0, 0); __builtin_amdgcn_s_setprio(0); } while (0)
; #define PG8_WAIT_V(n) asm volatile("s_waitcnt vmcnt(" #n ")" ::: "memory")
; #define PG8_WAIT_L(n) asm volatile("s_waitcnt lgkmcnt(" #n ")" ::: "memory")
; #define PG8_BAR __builtin_amdgcn_s_barrier()
; #define PG8_SCHED __builtin_amdgcn_sched_barrier(0)
; template <class Epi, class Sched>
; __device__ __forceinline__ void gemm_phase(LAS unsigned char* lds, const Sched& S, const Epi& E) {
;     ...
;             const bool last = (t == nt - 2);
;             const char* a1 = cA + (size_t)(t + 1) * kstep;
;             const char* a2 = last ? nA : cA + (size_t)(t + 2) * kstep; const char* b2 = last ? nB : cB + (size_t)(t + 2) * kstep;
;             const char* a3 = a2 + kstep; const char* b3 = b2 + kstep;
;             const unsigned xA0 = last ? nvA0 : vA0, xA1 = last ? nvA1 : vA1, xB0 = last ? nvB0 : vB0, xB1 = last ? nvB1 : vB1;
;             const size_t xhA = last ? nhA : hA, xhB = last ? nhB : hB;
;     ...
;             PG8_BAR; PG8_WAIT_L(0); PG8_MMA(0, 1, At, B1); PG8_BAR;
;             PG8_LDA(At, 1, 1); PG8_STAGE(PG8_SA(1, 0), a3, xA0, xA1);
;             PG8_BAR; PG8_WAIT_L(0); PG8_MMA(1, 0, At, B0); PG8_BAR; PG8_SCHED;
;             PG8_STAGE(PG8_SB(1, 1), b3 + xhB, xB0, xB1);
;             PG8_WAIT_V(6); PG8_BAR; PG8_MMA(1, 1, At, B1); PG8_BAR;
	s_waitcnt lgkmcnt(0)
	s_setprio 1
	s_waitcnt lgkmcnt(0)
	v_mfma_f32_16x16x32_bf16 v[116:119], v[148:151], v[194:197], v[116:119]
	v_mfma_f32_16x16x32_bf16 v[108:111], v[230:233], v[194:197], v[108:111]
	v_mfma_f32_16x16x32_bf16 v[100:103], v[148:151], v[202:205], v[100:103]
	v_mfma_f32_16x16x32_bf16 v[92:95], v[230:233], v[202:205], v[92:95]
	v_mfma_f32_16x16x32_bf16 v[84:87], v[148:151], v[210:213], v[84:87]
	v_mfma_f32_16x16x32_bf16 v[76:79], v[230:233], v[210:213], v[76:79]
	v_mfma_f32_16x16x32_bf16 v[68:71], v[148:151], v[218:221], v[68:71]
	v_mfma_f32_16x16x32_bf16 v[64:67], v[230:233], v[218:221], v[64:67]
	v_mfma_f32_16x16x32_bf16 v[116:119], v[226:229], v[198:201], v[116:119]
	v_mfma_f32_16x16x32_bf16 v[108:111], v[234:237], v[198:201], v[108:111]
	v_mfma_f32_16x16x32_bf16 v[100:103], v[226:229], v[206:209], v[100:103]
	v_mfma_f32_16x16x32_bf16 v[92:95], v[234:237], v[206:209], v[92:95]
	v_mfma_f32_16x16x32_bf16 v[84:87], v[226:229], v[214:217], v[84:87]
	v_mfma_f32_16x16x32_bf16 v[76:79], v[234:237], v[214:217], v[76:79]
	v_mfma_f32_16x16x32_bf16 v[68:71], v[226:229], v[222:225], v[68:71]
	v_mfma_f32_16x16x32_bf16 v[64:67], v[234:237], v[222:225], v[64:67]
	s_setprio 0
	s_mov_b32 m0, s64
	v_lshl_add_u64 v[138:139], v[242:243], 0, s[44:45]
	s_barrier
	ds_read_b128 v[194:197], v143 offset:49152
	ds_read_b128 v[198:201], v143 offset:50176
	ds_read_b128 v[202:205], v143 offset:51200
	ds_read_b128 v[206:209], v143 offset:52224
	ds_read_b128 v[210:213], v143 offset:53248
	ds_read_b128 v[214:217], v143 offset:54272
	ds_read_b128 v[218:221], v143 offset:55296
	ds_read_b128 v[222:225], v143 offset:56320
	global_load_lds_dwordx4 v[138:139], off
	v_lshl_add_u64 v[138:139], v[244:245], 0, s[44:45]
	s_mov_b32 m0, s65
	s_nop 0
	global_load_lds_dwordx4 v[138:139], off
	s_barrier
	s_waitcnt lgkmcnt(0)
	s_setprio 1
	s_waitcnt lgkmcnt(0)
	v_mfma_f32_16x16x32_bf16 v[60:63], v[158:161], v[194:197], v[60:63]
	v_mfma_f32_16x16x32_bf16 v[56:59], v[186:189], v[194:197], v[56:59]
	v_mfma_f32_16x16x32_bf16 v[44:47], v[158:161], v[202:205], v[44:47]
	v_mfma_f32_16x16x32_bf16 v[40:43], v[186:189], v[202:205], v[40:43]
	v_mfma_f32_16x16x32_bf16 v[28:31], v[158:161], v[210:213], v[28:31]
	v_mfma_f32_16x16x32_bf16 v[24:27], v[186:189], v[210:213], v[24:27]
	v_mfma_f32_16x16x32_bf16 v[12:15], v[158:161], v[218:221], v[12:15]
	v_mfma_f32_16x16x32_bf16 v[8:11], v[186:189], v[218:221], v[8:11]
	v_mfma_f32_16x16x32_bf16 v[60:63], v[182:185], v[198:201], v[60:63]
	v_mfma_f32_16x16x32_bf16 v[56:59], v[190:193], v[198:201], v[56:59]
	v_mfma_f32_16x16x32_bf16 v[44:47], v[182:185], v[206:209], v[44:47]
	v_mfma_f32_16x16x32_bf16 v[40:43], v[190:193], v[206:209], v[40:43]
	v_mfma_f32_16x16x32_bf16 v[28:31], v[182:185], v[214:217], v[28:31]
	v_mfma_f32_16x16x32_bf16 v[24:27], v[190:193], v[214:217], v[24:27]
	v_mfma_f32_16x16x32_bf16 v[12:15], v[182:185], v[222:225], v[12:15]
	v_mfma_f32_16x16x32_bf16 v[8:11], v[190:193], v[222:225], v[8:11]
	s_setprio 0
	s_barrier
	s_add_u32 s38, s38, 0x80080
	s_addc_u32 s39, s39, 0
	s_add_i32 s21, s40, s43
	s_mov_b32 m0, s21
	s_nop 0
	global_load_lds_dwordx4 v136, s[38:39]
	s_add_i32 m0, s21, 0x2000
	s_nop 0
	global_load_lds_dwordx4 v146, s[38:39]
	s_waitcnt vmcnt(6)
	s_barrier
	s_setprio 1
	v_mfma_f32_16x16x32_bf16 v[52:55], v[148:151], v[194:197], v[52:55]
	v_mfma_f32_16x16x32_bf16 v[48:51], v[230:233], v[194:197], v[48:51]
	v_mfma_f32_16x16x32_bf16 v[36:39], v[148:151], v[202:205], v[36:39]
	v_mfma_f32_16x16x32_bf16 v[32:35], v[230:233], v[202:205], v[32:35]
	v_mfma_f32_16x16x32_bf16 v[20:23], v[148:151], v[210:213], v[20:23]
	v_mfma_f32_16x16x32_bf16 v[16:19], v[230:233], v[210:213], v[16:19]
	v_mfma_f32_16x16x32_bf16 v[4:7], v[148:151], v[218:221], v[4:7]
	v_mfma_f32_16x16x32_bf16 v[0:3], v[230:233], v[218:221], v[0:3]
	v_mfma_f32_16x16x32_bf16 v[52:55], v[226:229], v[198:201], v[52:55]
	v_mfma_f32_16x16x32_bf16 v[48:51], v[234:237], v[198:201], v[48:51]
	v_mfma_f32_16x16x32_bf16 v[36:39], v[226:229], v[206:209], v[36:39]
	v_mfma_f32_16x16x32_bf16 v[32:35], v[234:237], v[206:209], v[32:35]
	v_mfma_f32_16x16x32_bf16 v[20:23], v[226:229], v[214:217], v[20:23]
	v_mfma_f32_16x16x32_bf16 v[16:19], v[234:237], v[214:217], v[16:19]
	v_mfma_f32_16x16x32_bf16 v[4:7], v[226:229], v[222:225], v[4:7]
	v_mfma_f32_16x16x32_bf16 v[0:3], v[234:237], v[222:225], v[0:3]
	s_setprio 0
	s_add_i32 s15, s15, 2
	s_add_u32 s26, s26, 0x100
	s_addc_u32 s27, s27, 0
	s_add_u32 s34, s34, 0x100
	s_addc_u32 s35, s35, 0
	s_cmp_gt_u32 s15, 29
	s_cbranch_scc1 .Lrot_exit_3
	s_cmp_eq_u32 s15, 28
	s_cselect_b64 s[40:41], -1, 0
	s_and_b64 vcc, exec, s[40:41]
	v_mov_b64_e32 v[148:149], v[130:131]
	v_mov_b64_e32 v[150:151], v[128:129]
	v_mov_b32_e32 v146, v156
	v_mov_b32_e32 v136, v145
	s_mov_b64 s[38:39], s[24:25]
	s_cbranch_vccnz .Lrot_join_3
	v_mov_b64_e32 v[148:149], v[134:135]
	v_mov_b64_e32 v[150:151], v[132:133]
	v_mov_b32_e32 v146, v142
	v_mov_b32_e32 v136, v144
	s_mov_b64 s[38:39], s[34:35]

; #define PG8_STAGE(bufoff, gbase, v0, v1) do { \
;         __builtin_amdgcn_global_load_lds((const unsigned*)((const char*)(gbase) + (v0)), (LAS unsigned*)(lds + (bufoff) + ldsw), 16, 0, 0); \
;         __builtin_amdgcn_global_load_lds((const unsigned*)((const char*)(gbase) + (v1)), (LAS unsigned*)(lds + (bufoff) + ldsw + 8192), 16, 0, 0); } while (0)
; #define PG8_LDA(dst, b, h) do { _Pragma("unroll") for (int m = 0; m < 4; ++m) _Pragma("unroll") for (int k = 0; k < 2; ++k) dst[m][k] = *(const LAS bf16x8*)(lds + PG8_SA(b, h) + aoff + m * 2048 + k * 1024); } while (0)
; #define PG8_LDB(dst, b, h) do { _Pragma("unroll") for (int n = 0; n < 2; ++n) _Pragma("unroll") for (int k = 0; k < 2; ++k) dst[n][k] = *(const LAS bf16x8*)(lds + PG8_SB(b, h) + boff + n * 2048 + k * 1024); } while (0)
; #define PG8_MMA(ai, bj, At, Bt) do { __builtin_amdgcn_s_setprio(1); _Pragma("unroll") for (int m = 0; m < 4; ++m) _Pragma("unroll") for (int n = 0; n < 2; ++n) _Pragma("unroll") for (int k = 0; k < 2; ++k) \
;         acc[ai][bj][m][n] = __builtin_amdgcn_mfma_f32_16x16x32_bf16(Bt[n][k], At[m][k], acc[ai][bj][m][n], 0, 0, 0); __builtin_amdgcn_s_setprio(0); } while (0)
; #define PG8_WAIT_L(n) asm volatile("s_waitcnt lgkmcnt(" #n ")" ::: "memory")
; template <class Epi, class Sched>
; __device__ __forceinline__ void gemm_phase(LAS unsigned char* lds, const Sched& S, const Epi& E) {
;     ...
;             const bool last = (t == nt - 2);
;             const char* a1 = cA + (size_t)(t + 1) * kstep;
;             const char* a2 = last ? nA : cA + (size_t)(t + 2) * kstep; const char* b2 = last ? nB : cB + (size_t)(t + 2) * kstep;
;             const char* a3 = a2 + kstep; const char* b3 = b2 + kstep;
;             const unsigned xA0 = last ? nvA0 : vA0, xA1 = last ? nvA1 : vA1, xB0 = last ? nvB0 : vB0, xB1 = last ? nvB1 : vB1;
;             const size_t xhA = last ? nhA : hA, xhB = last ? nhB : hB;
;             PG8_LDB(B0, 0, 0); PG8_SCHED; PG8_LDA(At, 0, 0); PG8_STAGE(PG8_SA(1, 1), a1 + hA, vA0, vA1);
;             PG8_WAIT_L(8); PG8_BAR; PG8_WAIT_L(0); PG8_MMA(0, 0, At, B0); PG8_BAR; PG8_SCHED;
;             PG8_LDB(B1, 0, 1); PG8_STAGE(PG8_SB(0, 0), b2, xB0, xB1);
;             PG8_BAR; PG8_WAIT_L(0); PG8_MMA(0, 1, At, B1); PG8_BAR;
;             PG8_LDA(At, 0, 1); PG8_STAGE(PG8_SA(0, 0), a2, xA0, xA1);
;             PG8_BAR; PG8_WAIT_L(0); PG8_MMA(1, 0, At, B0); PG8_BAR; PG8_SCHED;
.LBB0_847:
	s_add_u32 s15, s24, 0xffe00080
	s_addc_u32 s70, s25, -1
	s_and_b64 s[38:39], exec, s[38:39]
	s_cselect_b32 s39, s21, s70
	s_cselect_b32 s38, s20, s15
	s_add_i32 s15, 0, 0x10000
	v_add_u32_e32 v138, s15, v147
	ds_read_b128 v[150:153], v138
	ds_read_b128 v[154:157], v138 offset:1024
	ds_read_b128 v[158:161], v138 offset:2048
	ds_read_b128 v[182:185], v138 offset:3072
	v_lshl_add_u64 v[138:139], s[24:25], 0, v[136:137]
	s_add_i32 m0, s49, 0xc000
	ds_read_b128 v[186:189], v148
	ds_read_b128 v[190:193], v148 offset:1024
	ds_read_b128 v[194:197], v148 offset:2048
	ds_read_b128 v[198:201], v148 offset:3072
	ds_read_b128 v[202:205], v148 offset:4096
	ds_read_b128 v[206:209], v148 offset:5120
	ds_read_b128 v[210:213], v148 offset:6144
	ds_read_b128 v[214:217], v148 offset:7168
	global_load_lds_dwordx4 v[138:139], off
	v_lshl_add_u64 v[138:139], s[24:25], 0, v[132:133]
	s_add_i32 m0, s49, 0xe000
	s_nop 0
	global_load_lds_dwordx4 v[138:139], off
	s_waitcnt lgkmcnt(8)
	s_barrier
	s_waitcnt lgkmcnt(0)
	s_setprio 1
	s_waitcnt lgkmcnt(0)
	v_mfma_f32_16x16x32_bf16 v[124:127], v[150:153], v[186:189], v[124:127]
	v_mfma_f32_16x16x32_bf16 v[120:123], v[158:161], v[186:189], v[120:123]
	v_mfma_f32_16x16x32_bf16 v[108:111], v[150:153], v[194:197], v[108:111]
	v_mfma_f32_16x16x32_bf16 v[104:107], v[158:161], v[194:197], v[104:107]
	v_mfma_f32_16x16x32_bf16 v[100:103], v[150:153], v[202:205], v[100:103]
	v_mfma_f32_16x16x32_bf16 v[96:99], v[158:161], v[202:205], v[96:99]
	v_mfma_f32_16x16x32_bf16 v[84:87], v[150:153], v[210:213], v[84:87]
	v_mfma_f32_16x16x32_bf16 v[80:83], v[158:161], v[210:213], v[80:83]
	v_mfma_f32_16x16x32_bf16 v[124:127], v[154:157], v[190:193], v[124:127]
	v_mfma_f32_16x16x32_bf16 v[120:123], v[182:185], v[190:193], v[120:123]
	v_mfma_f32_16x16x32_bf16 v[108:111], v[154:157], v[198:201], v[108:111]
	v_mfma_f32_16x16x32_bf16 v[104:107], v[182:185], v[198:201], v[104:107]
	v_mfma_f32_16x16x32_bf16 v[100:103], v[154:157], v[206:209], v[100:103]
	v_mfma_f32_16x16x32_bf16 v[96:99], v[182:185], v[206:209], v[96:99]
	v_mfma_f32_16x16x32_bf16 v[84:87], v[154:157], v[214:217], v[84:87]
	v_mfma_f32_16x16x32_bf16 v[80:83], v[182:185], v[214:217], v[80:83]
	s_setprio 0
	s_barrier
	s_add_i32 s82, 0, 0x14000
	v_add_u32_e32 v138, s82, v147
	s_add_i32 s15, s15, s48
	ds_read_b128 v[218:221], v138
	ds_read_b128 v[222:225], v138 offset:1024
	ds_read_b128 v[226:229], v138 offset:2048
	ds_read_b128 v[230:233], v138 offset:3072
	v_lshl_add_u64 v[138:139], s[34:35], 0, v[142:143]
	s_mov_b32 m0, s15
	v_lshl_add_u64 v[140:141], s[34:35], 0, v[134:135]
	global_load_lds_dwordx4 v[138:139], off
	s_add_i32 m0, s15, 0x2000
	s_nop 0
	global_load_lds_dwordx4 v[140:141], off
	s_barrier
	s_waitcnt lgkmcnt(0)
	s_setprio 1
	s_waitcnt lgkmcnt(0)
	v_mfma_f32_16x16x32_bf16 v[116:119], v[218:221], v[186:189], v[116:119]
	v_mfma_f32_16x16x32_bf16 v[112:115], v[226:229], v[186:189], v[112:115]
	v_mfma_f32_16x16x32_bf16 v[92:95], v[218:221], v[194:197], v[92:95]
	v_mfma_f32_16x16x32_bf16 v[88:91], v[226:229], v[194:197], v[88:91]
	v_mfma_f32_16x16x32_bf16 v[76:79], v[218:221], v[202:205], v[76:79]
	v_mfma_f32_16x16x32_bf16 v[72:75], v[226:229], v[202:205], v[72:75]
	v_mfma_f32_16x16x32_bf16 v[68:71], v[218:221], v[210:213], v[68:71]
	v_mfma_f32_16x16x32_bf16 v[64:67], v[226:229], v[210:213], v[64:67]
	v_mfma_f32_16x16x32_bf16 v[116:119], v[222:225], v[190:193], v[116:119]
	v_mfma_f32_16x16x32_bf16 v[112:115], v[230:233], v[190:193], v[112:115]
	v_mfma_f32_16x16x32_bf16 v[92:95], v[222:225], v[198:201], v[92:95]
	v_mfma_f32_16x16x32_bf16 v[88:91], v[230:233], v[198:201], v[88:91]
	v_mfma_f32_16x16x32_bf16 v[76:79], v[222:225], v[206:209], v[76:79]
	v_mfma_f32_16x16x32_bf16 v[72:75], v[230:233], v[206:209], v[72:75]
	v_mfma_f32_16x16x32_bf16 v[68:71], v[222:225], v[214:217], v[68:71]
	v_mfma_f32_16x16x32_bf16 v[64:67], v[230:233], v[214:217], v[64:67]
	s_setprio 0
	s_mov_b32 m0, s49
	v_lshl_add_u64 v[234:235], s[38:39], 0, v[142:143]
	s_barrier
	ds_read_b128 v[186:189], v148 offset:16384
	ds_read_b128 v[190:193], v148 offset:17408
	ds_read_b128 v[194:197], v148 offset:18432
	ds_read_b128 v[198:201], v148 offset:19456
	ds_read_b128 v[202:205], v148 offset:20480
	ds_read_b128 v[206:209], v148 offset:21504
	ds_read_b128 v[210:213], v148 offset:22528
	ds_read_b128 v[214:217], v148 offset:23552
	global_load_lds_dwordx4 v[234:235], off
	v_lshl_add_u64 v[236:237], s[38:39], 0, v[134:135]
	s_mov_b32 m0, s50
	s_nop 0
	global_load_lds_dwordx4 v[236:237], off
	s_barrier
	s_waitcnt lgkmcnt(0)
	s_setprio 1
	s_waitcnt lgkmcnt(0)
	v_mfma_f32_16x16x32_bf16 v[60:63], v[150:153], v[186:189], v[60:63]
	v_mfma_f32_16x16x32_bf16 v[56:59], v[158:161], v[186:189], v[56:59]
	v_mfma_f32_16x16x32_bf16 v[44:47], v[150:153], v[194:197], v[44:47]
	v_mfma_f32_16x16x32_bf16 v[40:43], v[158:161], v[194:197], v[40:43]
	v_mfma_f32_16x16x32_bf16 v[28:31], v[150:153], v[202:205], v[28:31]
	v_mfma_f32_16x16x32_bf16 v[24:27], v[158:161], v[202:205], v[24:27]
	v_mfma_f32_16x16x32_bf16 v[12:15], v[150:153], v[210:213], v[12:15]
	v_mfma_f32_16x16x32_bf16 v[8:11], v[158:161], v[210:213], v[8:11]
	v_mfma_f32_16x16x32_bf16 v[60:63], v[154:157], v[190:193], v[60:63]
	v_mfma_f32_16x16x32_bf16 v[56:59], v[182:185], v[190:193], v[56:59]
	v_mfma_f32_16x16x32_bf16 v[44:47], v[154:157], v[198:201], v[44:47]
	v_mfma_f32_16x16x32_bf16 v[40:43], v[182:185], v[198:201], v[40:43]
	v_mfma_f32_16x16x32_bf16 v[28:31], v[154:157], v[206:209], v[28:31]
	v_mfma_f32_16x16x32_bf16 v[24:27], v[182:185], v[206:209], v[24:27]
	v_mfma_f32_16x16x32_bf16 v[12:15], v[154:157], v[214:217], v[12:15]
	v_mfma_f32_16x16x32_bf16 v[8:11], v[182:185], v[214:217], v[8:11]
	s_setprio 0
	s_barrier
; #define PG8_STAGE(bufoff, gbase, v0, v1) do { \
;         __builtin_amdgcn_global_load_lds((const unsigned*)((const char*)(gbase) + (v0)), (LAS unsigned*)(lds + (bufoff) + ldsw), 16, 0, 0); \
;         __builtin_amdgcn_global_load_lds((const unsigned*)((const char*)(gbase) + (v1)), (LAS unsigned*)(lds + (bufoff) + ldsw + 8192), 16, 0, 0); } while (0)
; #define PG8_LDA(dst, b, h) do { _Pragma("unroll") for (int m = 0; m < 4; ++m) _Pragma("unroll") for (int k = 0; k < 2; ++k) dst[m][k] = *(const LAS bf16x8*)(lds + PG8_SA(b, h) + aoff + m * 2048 + k * 1024); } while (0)
; #define PG8_LDB(dst, b, h) do { _Pragma("unroll") for (int n = 0; n < 2; ++n) _Pragma("unroll") for (int k = 0; k < 2; ++k) dst[n][k] = *(const LAS bf16x8*)(lds + PG8_SB(b, h) + boff + n * 2048 + k * 1024); } while (0)
; #define PG8_MMA(ai, bj, At, Bt) do { __builtin_amdgcn_s_setprio(1); _Pragma("unroll") for (int m = 0; m < 4; ++m) _Pragma("unroll") for (int n = 0; n < 2; ++n) _Pragma("unroll") for (int k = 0; k < 2; ++k) \
;         acc[ai][bj][m][n] = __builtin_amdgcn_mfma_f32_16x16x32_bf16(Bt[n][k], At[m][k], acc[ai][bj][m][n], 0, 0, 0); __builtin_amdgcn_s_setprio(0); } while (0)
; #define PG8_WAIT_V(n) asm volatile("s_waitcnt vmcnt(" #n ")" ::: "memory")
; #define PG8_WAIT_L(n) asm volatile("s_waitcnt lgkmcnt(" #n ")" ::: "memory")
; #define PG8_BAR __builtin_amdgcn_s_barrier()
; #define PG8_SCHED __builtin_amdgcn_sched_barrier(0)
; template <class Epi, class Sched>
; __device__ __forceinline__ void gemm_phase(LAS unsigned char* lds, const Sched& S, const Epi& E) {
;     ...
;             PG8_STAGE(PG8_SB(0, 1), b2 + xhB, xB0, xB1);
;             PG8_WAIT_V(6); PG8_BAR; PG8_MMA(1, 1, At, B1); PG8_BAR;
;             PG8_LDB(B0, 1, 0); PG8_SCHED; PG8_LDA(At, 1, 0); PG8_STAGE(PG8_SA(0, 1), a2 + xhA, xA0, xA1);
;             PG8_WAIT_L(8); PG8_BAR; PG8_WAIT_L(0); PG8_MMA(0, 0, At, B0); PG8_BAR; PG8_SCHED;
;             PG8_LDB(B1, 1, 1); PG8_STAGE(PG8_SB(1, 0), b3, xB0, xB1);
	s_add_u32 s70, s34, 0x200000
	s_addc_u32 s71, s35, 0
	s_add_i32 s15, s82, s48
	v_lshl_add_u64 v[150:151], s[70:71], 0, v[142:143]
	s_mov_b32 m0, s15
	s_nop 0
	global_load_lds_dwordx4 v[150:151], off
	v_lshl_add_u64 v[150:151], s[70:71], 0, v[134:135]
	s_add_i32 m0, s15, 0x2000
	s_nop 0
	global_load_lds_dwordx4 v[150:151], off
	s_waitcnt vmcnt(6)
	s_barrier
	s_setprio 1
	v_mfma_f32_16x16x32_bf16 v[52:55], v[218:221], v[186:189], v[52:55]
	v_mfma_f32_16x16x32_bf16 v[48:51], v[226:229], v[186:189], v[48:51]
	v_mfma_f32_16x16x32_bf16 v[36:39], v[218:221], v[194:197], v[36:39]
	v_mfma_f32_16x16x32_bf16 v[32:35], v[226:229], v[194:197], v[32:35]
	v_mfma_f32_16x16x32_bf16 v[20:23], v[218:221], v[202:205], v[20:23]
	v_mfma_f32_16x16x32_bf16 v[16:19], v[226:229], v[202:205], v[16:19]
	v_mfma_f32_16x16x32_bf16 v[4:7], v[218:221], v[210:213], v[4:7]
	v_mfma_f32_16x16x32_bf16 v[0:3], v[226:229], v[210:213], v[0:3]
	v_mfma_f32_16x16x32_bf16 v[52:55], v[222:225], v[190:193], v[52:55]
	v_mfma_f32_16x16x32_bf16 v[48:51], v[230:233], v[190:193], v[48:51]
	v_mfma_f32_16x16x32_bf16 v[36:39], v[222:225], v[198:201], v[36:39]
	v_mfma_f32_16x16x32_bf16 v[32:35], v[230:233], v[198:201], v[32:35]
	v_mfma_f32_16x16x32_bf16 v[20:23], v[222:225], v[206:209], v[20:23]
	v_mfma_f32_16x16x32_bf16 v[16:19], v[230:233], v[206:209], v[16:19]
	v_mfma_f32_16x16x32_bf16 v[4:7], v[222:225], v[214:217], v[4:7]
	v_mfma_f32_16x16x32_bf16 v[0:3], v[230:233], v[214:217], v[0:3]
	s_setprio 0
	s_add_i32 s15, 0, 0x18000
	v_add_u32_e32 v149, s15, v147
	s_barrier
	ds_read_b128 v[150:153], v149
	ds_read_b128 v[154:157], v149 offset:1024
	ds_read_b128 v[158:161], v149 offset:2048
	ds_read_b128 v[182:185], v149 offset:3072
	s_add_u32 s38, s38, 0x200000
	s_addc_u32 s39, s39, 0
	s_mov_b32 m0, s51
	v_lshl_add_u64 v[218:219], s[38:39], 0, v[142:143]
	ds_read_b128 v[186:189], v148 offset:32768
	ds_read_b128 v[190:193], v148 offset:33792
	ds_read_b128 v[194:197], v148 offset:34816
	ds_read_b128 v[198:201], v148 offset:35840
	ds_read_b128 v[202:205], v148 offset:36864
	ds_read_b128 v[206:209], v148 offset:37888
	ds_read_b128 v[210:213], v148 offset:38912
	ds_read_b128 v[214:217], v148 offset:39936
	global_load_lds_dwordx4 v[218:219], off
	v_lshl_add_u64 v[218:219], s[38:39], 0, v[134:135]
	s_mov_b32 m0, s54
	s_nop 0
	global_load_lds_dwordx4 v[218:219], off
	s_waitcnt lgkmcnt(8)
	s_barrier
	s_waitcnt lgkmcnt(0)
	s_setprio 1
	s_waitcnt lgkmcnt(0)
	v_mfma_f32_16x16x32_bf16 v[124:127], v[150:153], v[186:189], v[124:127]
	v_mfma_f32_16x16x32_bf16 v[120:123], v[158:161], v[186:189], v[120:123]
	v_mfma_f32_16x16x32_bf16 v[108:111], v[150:153], v[194:197], v[108:111]
	v_mfma_f32_16x16x32_bf16 v[104:107], v[158:161], v[194:197], v[104:107]
	v_mfma_f32_16x16x32_bf16 v[100:103], v[150:153], v[202:205], v[100:103]
	v_mfma_f32_16x16x32_bf16 v[96:99], v[158:161], v[202:205], v[96:99]
	v_mfma_f32_16x16x32_bf16 v[84:87], v[150:153], v[210:213], v[84:87]
	v_mfma_f32_16x16x32_bf16 v[80:83], v[158:161], v[210:213], v[80:83]
	v_mfma_f32_16x16x32_bf16 v[124:127], v[154:157], v[190:193], v[124:127]
	v_mfma_f32_16x16x32_bf16 v[120:123], v[182:185], v[190:193], v[120:123]
	v_mfma_f32_16x16x32_bf16 v[108:111], v[154:157], v[198:201], v[108:111]
	v_mfma_f32_16x16x32_bf16 v[104:107], v[182:185], v[198:201], v[104:107]
	v_mfma_f32_16x16x32_bf16 v[100:103], v[154:157], v[206:209], v[100:103]
	v_mfma_f32_16x16x32_bf16 v[96:99], v[182:185], v[206:209], v[96:99]
	v_mfma_f32_16x16x32_bf16 v[84:87], v[154:157], v[214:217], v[84:87]
	v_mfma_f32_16x16x32_bf16 v[80:83], v[182:185], v[214:217], v[80:83]
	s_setprio 0
	s_barrier
	s_add_i32 s38, 0, 0x1c000
	s_add_i32 s15, s15, s48
	v_add_u32_e32 v149, s38, v147
	v_lshl_add_u64 v[138:139], v[138:139], 0, s[44:45]
	s_mov_b32 m0, s15
	ds_read_b128 v[218:221], v149
	ds_read_b128 v[222:225], v149 offset:1024
	ds_read_b128 v[226:229], v149 offset:2048
	ds_read_b128 v[230:233], v149 offset:3072
	global_load_lds_dwordx4 v[138:139], off
	v_lshl_add_u64 v[138:139], v[140:141], 0, s[44:45]
	s_add_i32 m0, s15, 0x2000
	s_nop 0
	global_load_lds_dwordx4 v[138:139], off
	s_barrier
; #define PG8_STAGE(bufoff, gbase, v0, v1) do { \
;         __builtin_amdgcn_global_load_lds((const unsigned*)((const char*)(gbase) + (v0)), (LAS unsigned*)(lds + (bufoff) + ldsw), 16, 0, 0); \
;         __builtin_amdgcn_global_load_lds((const unsigned*)((const char*)(gbase) + (v1)), (LAS unsigned*)(lds + (bufoff) + ldsw + 8192), 16, 0, 0); } while (0)
; #define PG8_LDA(dst, b, h) do { _Pragma("unroll") for (int m = 0; m < 4; ++m) _Pragma("unroll") for (int k = 0; k < 2; ++k) dst[m][k] = *(const LAS bf16x8*)(lds + PG8_SA(b, h) + aoff + m * 2048 + k * 1024); } while (0)
; #define PG8_MMA(ai, bj, At, Bt) do { __builtin_amdgcn_s_setprio(1); _Pragma("unroll") for (int m = 0; m < 4; ++m) _Pragma("unroll") for (int n = 0; n < 2; ++n) _Pragma("unroll") for (int k = 0; k < 2; ++k) \
;         acc[ai][bj][m][n] = __builtin_amdgcn_mfma_f32_16x16x32_bf16(Bt[n][k], At[m][k], acc[ai][bj][m][n], 0, 0, 0); __builtin_amdgcn_s_setprio(0); } while (0)
; #define PG8_WAIT_V(n) asm volatile("s_waitcnt vmcnt(" #n ")" ::: "memory")
; #define PG8_WAIT_L(n) asm volatile("s_waitcnt lgkmcnt(" #n ")" ::: "memory")
; #define PG8_BAR __builtin_amdgcn_s_barrier()
; #define PG8_SCHED __builtin_amdgcn_sched_barrier(0)
; template <class Epi, class Sched>
; __device__ __forceinline__ void gemm_phase(LAS unsigned char* lds, const Sched& S, const Epi& E) {
;     ...
;             const bool last = (t == nt - 2);
;             const char* a1 = cA + (size_t)(t + 1) * kstep;
;             const char* a2 = last ? nA : cA + (size_t)(t + 2) * kstep; const char* b2 = last ? nB : cB + (size_t)(t + 2) * kstep;
;             const char* a3 = a2 + kstep; const char* b3 = b2 + kstep;
;             const unsigned xA0 = last ? nvA0 : vA0, xA1 = last ? nvA1 : vA1, xB0 = last ? nvB0 : vB0, xB1 = last ? nvB1 : vB1;
;             const size_t xhA = last ? nhA : hA, xhB = last ? nhB : hB;
;     ...
;             PG8_BAR; PG8_WAIT_L(0); PG8_MMA(0, 1, At, B1); PG8_BAR;
;             PG8_LDA(At, 1, 1); PG8_STAGE(PG8_SA(1, 0), a3, xA0, xA1);
;             PG8_BAR; PG8_WAIT_L(0); PG8_MMA(1, 0, At, B0); PG8_BAR; PG8_SCHED;
;             PG8_STAGE(PG8_SB(1, 1), b3 + xhB, xB0, xB1);
;             PG8_WAIT_V(6); PG8_BAR; PG8_MMA(1, 1, At, B1); PG8_BAR;
	s_waitcnt lgkmcnt(0)
	s_setprio 1
	s_waitcnt lgkmcnt(0)
	v_mfma_f32_16x16x32_bf16 v[116:119], v[218:221], v[186:189], v[116:119]
	v_mfma_f32_16x16x32_bf16 v[112:115], v[226:229], v[186:189], v[112:115]
	v_mfma_f32_16x16x32_bf16 v[92:95], v[218:221], v[194:197], v[92:95]
	v_mfma_f32_16x16x32_bf16 v[88:91], v[226:229], v[194:197], v[88:91]
	v_mfma_f32_16x16x32_bf16 v[76:79], v[218:221], v[202:205], v[76:79]
	v_mfma_f32_16x16x32_bf16 v[72:75], v[226:229], v[202:205], v[72:75]
	v_mfma_f32_16x16x32_bf16 v[68:71], v[218:221], v[210:213], v[68:71]
	v_mfma_f32_16x16x32_bf16 v[64:67], v[226:229], v[210:213], v[64:67]
	v_mfma_f32_16x16x32_bf16 v[116:119], v[222:225], v[190:193], v[116:119]
	v_mfma_f32_16x16x32_bf16 v[112:115], v[230:233], v[190:193], v[112:115]
	v_mfma_f32_16x16x32_bf16 v[92:95], v[222:225], v[198:201], v[92:95]
	v_mfma_f32_16x16x32_bf16 v[88:91], v[230:233], v[198:201], v[88:91]
	v_mfma_f32_16x16x32_bf16 v[76:79], v[222:225], v[206:209], v[76:79]
	v_mfma_f32_16x16x32_bf16 v[72:75], v[230:233], v[206:209], v[72:75]
	v_mfma_f32_16x16x32_bf16 v[68:71], v[222:225], v[214:217], v[68:71]
	v_mfma_f32_16x16x32_bf16 v[64:67], v[230:233], v[214:217], v[64:67]
	s_setprio 0
	s_mov_b32 m0, s65
	v_lshl_add_u64 v[138:139], v[234:235], 0, s[44:45]
	s_barrier
	ds_read_b128 v[186:189], v148 offset:49152
	ds_read_b128 v[190:193], v148 offset:50176
	ds_read_b128 v[194:197], v148 offset:51200
	ds_read_b128 v[198:201], v148 offset:52224
	ds_read_b128 v[202:205], v148 offset:53248
	ds_read_b128 v[206:209], v148 offset:54272
	ds_read_b128 v[210:213], v148 offset:55296
	ds_read_b128 v[214:217], v148 offset:56320
	global_load_lds_dwordx4 v[138:139], off
	v_lshl_add_u64 v[138:139], v[236:237], 0, s[44:45]
	s_mov_b32 m0, s66
	s_nop 0
	global_load_lds_dwordx4 v[138:139], off
	s_barrier
	s_waitcnt lgkmcnt(0)
	s_setprio 1
	s_waitcnt lgkmcnt(0)
	v_mfma_f32_16x16x32_bf16 v[60:63], v[150:153], v[186:189], v[60:63]
	v_mfma_f32_16x16x32_bf16 v[56:59], v[158:161], v[186:189], v[56:59]
	v_mfma_f32_16x16x32_bf16 v[44:47], v[150:153], v[194:197], v[44:47]
	v_mfma_f32_16x16x32_bf16 v[40:43], v[158:161], v[194:197], v[40:43]
	v_mfma_f32_16x16x32_bf16 v[28:31], v[150:153], v[202:205], v[28:31]
	v_mfma_f32_16x16x32_bf16 v[24:27], v[158:161], v[202:205], v[24:27]
	v_mfma_f32_16x16x32_bf16 v[12:15], v[150:153], v[210:213], v[12:15]
	v_mfma_f32_16x16x32_bf16 v[8:11], v[158:161], v[210:213], v[8:11]
	v_mfma_f32_16x16x32_bf16 v[60:63], v[154:157], v[190:193], v[60:63]
	v_mfma_f32_16x16x32_bf16 v[56:59], v[182:185], v[190:193], v[56:59]
	v_mfma_f32_16x16x32_bf16 v[44:47], v[154:157], v[198:201], v[44:47]
	v_mfma_f32_16x16x32_bf16 v[40:43], v[182:185], v[198:201], v[40:43]
	v_mfma_f32_16x16x32_bf16 v[28:31], v[154:157], v[206:209], v[28:31]
	v_mfma_f32_16x16x32_bf16 v[24:27], v[182:185], v[206:209], v[24:27]
	v_mfma_f32_16x16x32_bf16 v[12:15], v[154:157], v[214:217], v[12:15]
	v_mfma_f32_16x16x32_bf16 v[8:11], v[182:185], v[214:217], v[8:11]
	s_setprio 0
	s_barrier
	s_add_u32 s34, s34, 0x200080
	s_addc_u32 s35, s35, 0
	s_add_i32 s15, s38, s48
	v_lshl_add_u64 v[138:139], s[34:35], 0, v[142:143]
	s_mov_b32 m0, s15
	v_lshl_add_u64 v[134:135], s[34:35], 0, v[134:135]
	global_load_lds_dwordx4 v[138:139], off
	s_add_i32 m0, s15, 0x2000
	s_nop 0
	global_load_lds_dwordx4 v[134:135], off
	s_waitcnt vmcnt(6)
	s_barrier
	s_setprio 1
	v_mfma_f32_16x16x32_bf16 v[52:55], v[218:221], v[186:189], v[52:55]
	v_mfma_f32_16x16x32_bf16 v[48:51], v[226:229], v[186:189], v[48:51]
	v_mfma_f32_16x16x32_bf16 v[36:39], v[218:221], v[194:197], v[36:39]
	v_mfma_f32_16x16x32_bf16 v[32:35], v[226:229], v[194:197], v[32:35]
	v_mfma_f32_16x16x32_bf16 v[20:23], v[218:221], v[202:205], v[20:23]
	v_mfma_f32_16x16x32_bf16 v[16:19], v[226:229], v[202:205], v[16:19]
	v_mfma_f32_16x16x32_bf16 v[4:7], v[218:221], v[210:213], v[4:7]
	v_mfma_f32_16x16x32_bf16 v[0:3], v[226:229], v[210:213], v[0:3]
	v_mfma_f32_16x16x32_bf16 v[52:55], v[222:225], v[190:193], v[52:55]
	v_mfma_f32_16x16x32_bf16 v[48:51], v[230:233], v[190:193], v[48:51]
	v_mfma_f32_16x16x32_bf16 v[36:39], v[222:225], v[198:201], v[36:39]
	v_mfma_f32_16x16x32_bf16 v[32:35], v[230:233], v[198:201], v[32:35]
	v_mfma_f32_16x16x32_bf16 v[20:23], v[222:225], v[206:209], v[20:23]
	v_mfma_f32_16x16x32_bf16 v[16:19], v[230:233], v[206:209], v[16:19]
	v_mfma_f32_16x16x32_bf16 v[4:7], v[222:225], v[214:217], v[4:7]
	v_mfma_f32_16x16x32_bf16 v[0:3], v[230:233], v[214:217], v[0:3]
	s_setprio 0
	s_add_i32 s11, s11, 2
	s_add_u32 s24, s24, 0x100
	s_addc_u32 s25, s25, 0
	s_add_u32 s26, s26, 0x100
	s_addc_u32 s27, s27, 0
	s_cmpk_gt_u32 s11, 0x7d
	s_cbranch_scc1 .Lrot_exit_4
	s_cmpk_eq_i32 s11, 0x7c
	s_cselect_b64 s[38:39], -1, 0
	s_and_b64 vcc, exec, s[38:39]
	v_mov_b64_e32 v[134:135], v[130:131]
	v_mov_b64_e32 v[142:143], v[128:129]
	s_mov_b64 s[34:35], s[22:23]
	s_cbranch_vccnz .Lrot_join_4
	v_mov_b64_e32 v[134:135], v[132:133]
	v_mov_b64_e32 v[142:143], v[136:137]
	s_mov_b64 s[34:35], s[26:27]
